# scan stage 4b: epilogue-token LDS prefetch + forward substitution rewritten with v_pk_fma_f32 and ring-buffered Nab rows
# speedup vs baseline: 1.0259x; 1.0096x over previous
.LBB0_582:
	s_cmp_eq_u32 s85, 0
	s_cselect_b64 s[34:35], -1, 0
	s_or_b64 s[34:35], s[74:75], s[34:35]
	s_and_b64 vcc, exec, s[34:35]
	s_waitcnt lgkmcnt(0)
	s_barrier
	s_cbranch_vccnz .LBB0_585
	v_cndmask_b32_e64 v3, 0, 1, s[94:95]
	v_lshlrev_b32_e32 v3, 7, v3
	v_readlane_b32 s5, v250, 33
	s_mov_b32 s8, 0x9000
	v_mov_b32_e32 v38, v121
	v_add_u32_e32 v3, s5, v3
	s_add_i32 s5, s85, -1
	s_bitcmp0_b32 s5, 0
	s_movk_i32 s5, 0x6c00
	s_cselect_b32 s5, s5, 0x13600
	s_cselect_b32 s34, s8, 0x14800
	v_add_u32_e32 v4, s34, v120
	v_add_u32_e32 v5, s5, v120
	v_readlane_b32 s5, v250, 32
	ds_read_b32 v208, v38
	ds_read_b32 v209, v3
	ds_read_u16 v210, v5
	ds_read_u16 v211, v4
.LBB0_584:
	s_waitcnt lgkmcnt(0)
	v_mov_b32_e32 v39, v208
	v_mov_b32_e32 v86, v209
	v_mov_b32_e32 v212, v210
	v_mov_b32_e32 v213, v211
	v_add_u32_e32 v38, 0x700, v38
	v_add_u32_e32 v3, 28, v3
	v_add_u32_e32 v5, 0x3f0, v5
	v_add_u32_e32 v4, 0x3f0, v4
	ds_read_b32 v208, v38
	ds_read_b32 v209, v3
	ds_read_u16 v210, v5
	ds_read_u16 v211, v4
	v_add_f32_dpp v40, v39, v39 quad_perm:[1,0,3,2] row_mask:0xf bank_mask:0xf bound_ctrl:1
	s_nop 1
	v_add_f32_dpp v40, v40, v40 quad_perm:[2,3,0,1] row_mask:0xf bank_mask:0xf bound_ctrl:1
	s_nop 1
	v_add_f32_dpp v40, v40, v40 row_ror:4 row_mask:0xf bank_mask:0xf bound_ctrl:1
	s_nop 1
	v_add_f32_dpp v40, v40, v40 row_ror:8 row_mask:0xf bank_mask:0xf bound_ctrl:1
	s_nop 0
	v_readlane_b32 s85, v40, 16
	v_readlane_b32 s92, v40, 48
	v_readlane_b32 s34, v40, 0
	v_readlane_b32 s35, v40, 32
	v_mov_b32_e32 v40, s85
	v_mov_b32_e32 v41, s92
	v_pk_add_f32 v[40:41], s[34:35], v[40:41]
	s_nop 0
	v_add_f32_e32 v40, v40, v41
	v_fmac_f32_e32 v39, 0xbc800000, v40
	v_mul_f32_e32 v40, v39, v39
	s_nop 1
	v_mov_b32_dpp v40, v40 quad_perm:[1,0,3,2] row_mask:0xf bank_mask:0xf bound_ctrl:1
	v_fmac_f32_e32 v40, v39, v39
	s_nop 1
	v_add_f32_dpp v40, v40, v40 quad_perm:[2,3,0,1] row_mask:0xf bank_mask:0xf bound_ctrl:1
	s_nop 1
	v_add_f32_dpp v40, v40, v40 row_ror:4 row_mask:0xf bank_mask:0xf bound_ctrl:1
	s_nop 1
	v_add_f32_dpp v40, v40, v40 row_ror:8 row_mask:0xf bank_mask:0xf bound_ctrl:1
	s_nop 0
	v_readlane_b32 s85, v40, 16
	v_readlane_b32 s92, v40, 48
	v_readlane_b32 s34, v40, 0
	v_readlane_b32 s35, v40, 32
	v_mov_b32_e32 v40, s85
	v_mov_b32_e32 v41, s92
	v_pk_add_f32 v[40:41], s[34:35], v[40:41]
	s_add_i32 s34, s86, s5
	v_add_f32_e32 v40, v40, v41
	v_fmamk_f32 v40, v40, 0x3c800000, v128
	v_rsq_f32_e32 v40, v40
	s_ashr_i32 s35, s34, 31
	s_lshl_b64 s[34:35], s[34:35], 11
	v_mul_f32_e32 v41, v39, v40
	v_lshlrev_b32_e32 v40, 16, v212
	v_pk_mul_f32 v[40:41], v[86:87], v[40:41]
	s_nop 0
	v_add_f32_e32 v39, v142, v41
	v_add_f32_e32 v39, v40, v39
	v_lshlrev_b32_e32 v40, 16, v213
	v_mul_f32_e32 v39, v39, v40
	v_lshl_add_u64 v[40:41], v[88:89], 0, s[34:35]
	s_add_i32 s34, s5, 7
	s_add_i32 s5, s5, -1
	s_cmp_lt_i32 s5, 25
	s_mov_b32 s5, s34
	v_cvt_pk_bf16_f32 v39, v39, v2
	global_store_short v[40:41], v39, off
	s_cbranch_scc1 .LBB0_584
.LBB0_585:
	s_and_b64 vcc, exec, s[30:31]
	s_cbranch_vccnz .LBB0_587
	ds_read2st64_b32 v[176:177], v106 offset0:244 offset1:245
	ds_read2st64_b32 v[178:179], v106 offset0:246 offset1:247
	ds_read2st64_b32 v[180:181], v106 offset0:248 offset1:249
	ds_read2st64_b32 v[182:183], v106 offset0:250 offset1:251
	ds_read2st64_b32 v[184:185], v106 offset0:252 offset1:253
	ds_read2st64_b32 v[186:187], v106 offset0:254 offset1:255
	ds_read2st64_b32 v[188:189], v107 offset0:12 offset1:13
	ds_read2st64_b32 v[190:191], v107 offset0:14 offset1:15
	ds_read2st64_b32 v[192:193], v107 offset0:16 offset1:17
	ds_read2st64_b32 v[194:195], v107 offset0:18 offset1:19
	ds_read2st64_b32 v[196:197], v107 offset0:20 offset1:21
	ds_read2st64_b32 v[198:199], v107 offset0:22 offset1:23
	ds_read2st64_b32 v[200:201], v107 offset0:24 offset1:25
	ds_read2st64_b32 v[202:203], v107 offset0:26 offset1:27
	ds_read2st64_b32 v[204:205], v107 offset0:28 offset1:29
	s_waitcnt lgkmcnt(14)
	ds_read2st64_b32 v[206:207], v107 offset0:30 offset1:31
	s_waitcnt lgkmcnt(14)
	ds_read_b128 v[208:211], v2 offset:58368
	s_waitcnt lgkmcnt(14)
	ds_read_b128 v[212:215], v2 offset:58384
	s_waitcnt lgkmcnt(14)
	ds_read_b128 v[216:219], v2 offset:58400
	s_waitcnt lgkmcnt(14)
	ds_read_b128 v[220:223], v2 offset:58416
	s_waitcnt lgkmcnt(14)
	ds_read_b128 v[224:227], v2 offset:58432
	s_waitcnt lgkmcnt(14)
	ds_read_b128 v[228:231], v2 offset:58448
	s_waitcnt lgkmcnt(14)
	ds_read_b128 v[240:243], v2 offset:58464
	s_waitcnt lgkmcnt(14)
	ds_read_b128 v[244:247], v2 offset:58480
	s_waitcnt lgkmcnt(14)
	ds_read_b128 v[38:41], v2 offset:58496
	s_waitcnt lgkmcnt(14)
	ds_read_b128 v[42:45], v2 offset:58512
	s_waitcnt lgkmcnt(14)
	ds_read_b128 v[46:49], v2 offset:58528
	s_waitcnt lgkmcnt(14)
	ds_read_b128 v[50:53], v2 offset:58544
	s_waitcnt lgkmcnt(11)
	v_pk_fma_f32 v[176:177], v[208:209], v[176:177], v[176:177] op_sel:[0,0,0] op_sel_hi:[1,0,1]
	v_pk_fma_f32 v[178:179], v[210:211], v[176:177], v[178:179] op_sel:[0,0,0] op_sel_hi:[1,0,1]
	v_cvt_pk_bf16_f32 v3, v176, v2
	ds_write_b16 v108, v3 offset:32256
	ds_read_b128 v[208:211], v2 offset:58560
	s_waitcnt lgkmcnt(12)
	v_pk_fma_f32 v[180:181], v[212:213], v[176:177], v[180:181] op_sel:[0,0,0] op_sel_hi:[1,0,1]
	v_pk_fma_f32 v[182:183], v[214:215], v[176:177], v[182:183] op_sel:[0,0,0] op_sel_hi:[1,0,1]
	ds_read_b128 v[212:215], v2 offset:58576
	s_waitcnt lgkmcnt(12)
	v_pk_fma_f32 v[184:185], v[216:217], v[176:177], v[184:185] op_sel:[0,0,0] op_sel_hi:[1,0,1]
	v_pk_fma_f32 v[186:187], v[218:219], v[176:177], v[186:187] op_sel:[0,0,0] op_sel_hi:[1,0,1]
	ds_read_b128 v[216:219], v2 offset:58592
	s_waitcnt lgkmcnt(12)
	v_pk_fma_f32 v[188:189], v[220:221], v[176:177], v[188:189] op_sel:[0,0,0] op_sel_hi:[1,0,1]
	v_pk_fma_f32 v[190:191], v[222:223], v[176:177], v[190:191] op_sel:[0,0,0] op_sel_hi:[1,0,1]
	ds_read_b128 v[220:223], v2 offset:58608
	s_waitcnt lgkmcnt(12)
	v_pk_fma_f32 v[192:193], v[224:225], v[176:177], v[192:193] op_sel:[0,0,0] op_sel_hi:[1,0,1]
	v_pk_fma_f32 v[194:195], v[226:227], v[176:177], v[194:195] op_sel:[0,0,0] op_sel_hi:[1,0,1]
	ds_read_b128 v[224:227], v2 offset:58624
	s_waitcnt lgkmcnt(12)
	v_pk_fma_f32 v[196:197], v[228:229], v[176:177], v[196:197] op_sel:[0,0,0] op_sel_hi:[1,0,1]
	v_pk_fma_f32 v[198:199], v[230:231], v[176:177], v[198:199] op_sel:[0,0,0] op_sel_hi:[1,0,1]
	ds_read_b128 v[228:231], v2 offset:58640
	s_waitcnt lgkmcnt(12)
	v_pk_fma_f32 v[200:201], v[240:241], v[176:177], v[200:201] op_sel:[0,0,0] op_sel_hi:[1,0,1]
	v_pk_fma_f32 v[202:203], v[242:243], v[176:177], v[202:203] op_sel:[0,0,0] op_sel_hi:[1,0,1]
	ds_read_b128 v[240:243], v2 offset:58656
	s_waitcnt lgkmcnt(12)
	v_pk_fma_f32 v[204:205], v[244:245], v[176:177], v[204:205] op_sel:[0,0,0] op_sel_hi:[1,0,1]
	v_pk_fma_f32 v[206:207], v[246:247], v[176:177], v[206:207] op_sel:[0,0,0] op_sel_hi:[1,0,1]
	ds_read_b128 v[244:247], v2 offset:58672
	s_waitcnt lgkmcnt(12)
	v_pk_fma_f32 v[178:179], v[40:41], v[176:177], v[178:179] op_sel:[0,1,0] op_sel_hi:[1,1,1]
	v_cvt_pk_bf16_f32 v232, v177, v2
	ds_write_b16 v108, v232 offset:32400
	ds_read_b128 v[38:41], v2 offset:58688
	s_waitcnt lgkmcnt(13)
	v_pk_fma_f32 v[180:181], v[42:43], v[176:177], v[180:181] op_sel:[0,1,0] op_sel_hi:[1,1,1]
	v_pk_fma_f32 v[182:183], v[44:45], v[176:177], v[182:183] op_sel:[0,1,0] op_sel_hi:[1,1,1]
	ds_read_b128 v[42:45], v2 offset:58704
	s_waitcnt lgkmcnt(13)
	v_pk_fma_f32 v[184:185], v[46:47], v[176:177], v[184:185] op_sel:[0,1,0] op_sel_hi:[1,1,1]
	v_pk_fma_f32 v[186:187], v[48:49], v[176:177], v[186:187] op_sel:[0,1,0] op_sel_hi:[1,1,1]
	ds_read_b128 v[46:49], v2 offset:58720
	s_waitcnt lgkmcnt(13)
	v_pk_fma_f32 v[188:189], v[50:51], v[176:177], v[188:189] op_sel:[0,1,0] op_sel_hi:[1,1,1]
	v_pk_fma_f32 v[190:191], v[52:53], v[176:177], v[190:191] op_sel:[0,1,0] op_sel_hi:[1,1,1]
	ds_read_b128 v[50:53], v2 offset:58736
	s_waitcnt lgkmcnt(12)
	v_pk_fma_f32 v[192:193], v[208:209], v[176:177], v[192:193] op_sel:[0,1,0] op_sel_hi:[1,1,1]
	v_pk_fma_f32 v[194:195], v[210:211], v[176:177], v[194:195] op_sel:[0,1,0] op_sel_hi:[1,1,1]
	ds_read_b128 v[208:211], v2 offset:58768
	s_waitcnt lgkmcnt(12)
	v_pk_fma_f32 v[196:197], v[212:213], v[176:177], v[196:197] op_sel:[0,1,0] op_sel_hi:[1,1,1]
	v_pk_fma_f32 v[198:199], v[214:215], v[176:177], v[198:199] op_sel:[0,1,0] op_sel_hi:[1,1,1]
	ds_read_b128 v[212:215], v2 offset:58784
	s_waitcnt lgkmcnt(12)
	v_pk_fma_f32 v[200:201], v[216:217], v[176:177], v[200:201] op_sel:[0,1,0] op_sel_hi:[1,1,1]
	v_pk_fma_f32 v[202:203], v[218:219], v[176:177], v[202:203] op_sel:[0,1,0] op_sel_hi:[1,1,1]
	ds_read_b128 v[216:219], v2 offset:58800
	s_waitcnt lgkmcnt(12)
	v_pk_fma_f32 v[204:205], v[220:221], v[176:177], v[204:205] op_sel:[0,1,0] op_sel_hi:[1,1,1]
	v_pk_fma_f32 v[206:207], v[222:223], v[176:177], v[206:207] op_sel:[0,1,0] op_sel_hi:[1,1,1]
	ds_read_b128 v[220:223], v2 offset:58816
	s_waitcnt lgkmcnt(12)
	v_pk_fma_f32 v[178:179], v[226:227], v[178:179], v[178:179] op_sel:[0,0,0] op_sel_hi:[1,0,1]
	v_cvt_pk_bf16_f32 v233, v178, v2
	ds_write_b16 v108, v233 offset:32544
	ds_read_b128 v[224:227], v2 offset:58832
	s_waitcnt lgkmcnt(13)
	v_pk_fma_f32 v[180:181], v[228:229], v[178:179], v[180:181] op_sel:[0,0,0] op_sel_hi:[1,0,1]
	v_pk_fma_f32 v[182:183], v[230:231], v[178:179], v[182:183] op_sel:[0,0,0] op_sel_hi:[1,0,1]
	ds_read_b128 v[228:231], v2 offset:58848
	s_waitcnt lgkmcnt(13)
	v_pk_fma_f32 v[184:185], v[240:241], v[178:179], v[184:185] op_sel:[0,0,0] op_sel_hi:[1,0,1]
	v_pk_fma_f32 v[186:187], v[242:243], v[178:179], v[186:187] op_sel:[0,0,0] op_sel_hi:[1,0,1]
	ds_read_b128 v[240:243], v2 offset:58864
	s_waitcnt lgkmcnt(13)
	v_pk_fma_f32 v[188:189], v[244:245], v[178:179], v[188:189] op_sel:[0,0,0] op_sel_hi:[1,0,1]
	v_pk_fma_f32 v[190:191], v[246:247], v[178:179], v[190:191] op_sel:[0,0,0] op_sel_hi:[1,0,1]
	ds_read_b128 v[244:247], v2 offset:58896
	s_waitcnt lgkmcnt(12)
	v_pk_fma_f32 v[192:193], v[38:39], v[178:179], v[192:193] op_sel:[0,0,0] op_sel_hi:[1,0,1]
	v_pk_fma_f32 v[194:195], v[40:41], v[178:179], v[194:195] op_sel:[0,0,0] op_sel_hi:[1,0,1]
	ds_read_b128 v[38:41], v2 offset:58912
	s_waitcnt lgkmcnt(12)
	v_pk_fma_f32 v[196:197], v[42:43], v[178:179], v[196:197] op_sel:[0,0,0] op_sel_hi:[1,0,1]
	v_pk_fma_f32 v[198:199], v[44:45], v[178:179], v[198:199] op_sel:[0,0,0] op_sel_hi:[1,0,1]
	ds_read_b128 v[42:45], v2 offset:58928
	s_waitcnt lgkmcnt(12)
	v_pk_fma_f32 v[200:201], v[46:47], v[178:179], v[200:201] op_sel:[0,0,0] op_sel_hi:[1,0,1]
	v_pk_fma_f32 v[202:203], v[48:49], v[178:179], v[202:203] op_sel:[0,0,0] op_sel_hi:[1,0,1]
	ds_read_b128 v[46:49], v2 offset:58944
	s_waitcnt lgkmcnt(12)
	v_pk_fma_f32 v[204:205], v[50:51], v[178:179], v[204:205] op_sel:[0,0,0] op_sel_hi:[1,0,1]
	v_pk_fma_f32 v[206:207], v[52:53], v[178:179], v[206:207] op_sel:[0,0,0] op_sel_hi:[1,0,1]
	ds_read_b128 v[50:53], v2 offset:58960
	s_waitcnt lgkmcnt(12)
	v_pk_fma_f32 v[180:181], v[208:209], v[178:179], v[180:181] op_sel:[0,1,0] op_sel_hi:[1,1,1]
	v_pk_fma_f32 v[182:183], v[210:211], v[178:179], v[182:183] op_sel:[0,1,0] op_sel_hi:[1,1,1]
	v_cvt_pk_bf16_f32 v248, v179, v2
	ds_write_b16 v108, v248 offset:32688
	ds_read_b128 v[208:211], v2 offset:58976
	s_waitcnt lgkmcnt(13)
	v_pk_fma_f32 v[184:185], v[212:213], v[178:179], v[184:185] op_sel:[0,1,0] op_sel_hi:[1,1,1]
	v_pk_fma_f32 v[186:187], v[214:215], v[178:179], v[186:187] op_sel:[0,1,0] op_sel_hi:[1,1,1]
	ds_read_b128 v[212:215], v2 offset:58992
	s_waitcnt lgkmcnt(13)
	v_pk_fma_f32 v[188:189], v[216:217], v[178:179], v[188:189] op_sel:[0,1,0] op_sel_hi:[1,1,1]
	v_pk_fma_f32 v[190:191], v[218:219], v[178:179], v[190:191] op_sel:[0,1,0] op_sel_hi:[1,1,1]
	ds_read_b128 v[216:219], v2 offset:59024
	s_waitcnt lgkmcnt(13)
	v_pk_fma_f32 v[192:193], v[220:221], v[178:179], v[192:193] op_sel:[0,1,0] op_sel_hi:[1,1,1]
	v_pk_fma_f32 v[194:195], v[222:223], v[178:179], v[194:195] op_sel:[0,1,0] op_sel_hi:[1,1,1]
	ds_read_b128 v[220:223], v2 offset:59040
	s_waitcnt lgkmcnt(12)
	v_pk_fma_f32 v[196:197], v[224:225], v[178:179], v[196:197] op_sel:[0,1,0] op_sel_hi:[1,1,1]
	v_pk_fma_f32 v[198:199], v[226:227], v[178:179], v[198:199] op_sel:[0,1,0] op_sel_hi:[1,1,1]
	ds_read_b128 v[224:227], v2 offset:59056
	s_waitcnt lgkmcnt(12)
	v_pk_fma_f32 v[200:201], v[228:229], v[178:179], v[200:201] op_sel:[0,1,0] op_sel_hi:[1,1,1]
	v_pk_fma_f32 v[202:203], v[230:231], v[178:179], v[202:203] op_sel:[0,1,0] op_sel_hi:[1,1,1]
	ds_read_b128 v[228:231], v2 offset:59072
	s_waitcnt lgkmcnt(12)
	v_pk_fma_f32 v[204:205], v[240:241], v[178:179], v[204:205] op_sel:[0,1,0] op_sel_hi:[1,1,1]
	v_pk_fma_f32 v[206:207], v[242:243], v[178:179], v[206:207] op_sel:[0,1,0] op_sel_hi:[1,1,1]
	ds_read_b128 v[240:243], v2 offset:59088
	s_waitcnt lgkmcnt(12)
	v_pk_fma_f32 v[180:181], v[244:245], v[180:181], v[180:181] op_sel:[0,0,0] op_sel_hi:[1,0,1]
	v_pk_fma_f32 v[182:183], v[246:247], v[180:181], v[182:183] op_sel:[0,0,0] op_sel_hi:[1,0,1]
	v_cvt_pk_bf16_f32 v3, v180, v2
	ds_write_b16 v108, v3 offset:32832
	ds_read_b128 v[244:247], v2 offset:59104
	s_waitcnt lgkmcnt(13)
	v_pk_fma_f32 v[184:185], v[38:39], v[180:181], v[184:185] op_sel:[0,0,0] op_sel_hi:[1,0,1]
	v_pk_fma_f32 v[186:187], v[40:41], v[180:181], v[186:187] op_sel:[0,0,0] op_sel_hi:[1,0,1]
	ds_read_b128 v[38:41], v2 offset:59120
	s_waitcnt lgkmcnt(13)
	v_pk_fma_f32 v[188:189], v[42:43], v[180:181], v[188:189] op_sel:[0,0,0] op_sel_hi:[1,0,1]
	v_pk_fma_f32 v[190:191], v[44:45], v[180:181], v[190:191] op_sel:[0,0,0] op_sel_hi:[1,0,1]
	ds_read_b128 v[42:45], v2 offset:59152
	s_waitcnt lgkmcnt(13)
	v_pk_fma_f32 v[192:193], v[46:47], v[180:181], v[192:193] op_sel:[0,0,0] op_sel_hi:[1,0,1]
	v_pk_fma_f32 v[194:195], v[48:49], v[180:181], v[194:195] op_sel:[0,0,0] op_sel_hi:[1,0,1]
	ds_read_b128 v[46:49], v2 offset:59168
	s_waitcnt lgkmcnt(13)
	v_pk_fma_f32 v[196:197], v[50:51], v[180:181], v[196:197] op_sel:[0,0,0] op_sel_hi:[1,0,1]
	v_pk_fma_f32 v[198:199], v[52:53], v[180:181], v[198:199] op_sel:[0,0,0] op_sel_hi:[1,0,1]
	ds_read_b128 v[50:53], v2 offset:59184
	s_waitcnt lgkmcnt(12)
	v_pk_fma_f32 v[200:201], v[208:209], v[180:181], v[200:201] op_sel:[0,0,0] op_sel_hi:[1,0,1]
	v_pk_fma_f32 v[202:203], v[210:211], v[180:181], v[202:203] op_sel:[0,0,0] op_sel_hi:[1,0,1]
	ds_read_b128 v[208:211], v2 offset:59200
	s_waitcnt lgkmcnt(12)
	v_pk_fma_f32 v[204:205], v[212:213], v[180:181], v[204:205] op_sel:[0,0,0] op_sel_hi:[1,0,1]
	v_pk_fma_f32 v[206:207], v[214:215], v[180:181], v[206:207] op_sel:[0,0,0] op_sel_hi:[1,0,1]
	ds_read_b128 v[212:215], v2 offset:59216
	s_waitcnt lgkmcnt(12)
	v_pk_fma_f32 v[182:183], v[218:219], v[180:181], v[182:183] op_sel:[0,1,0] op_sel_hi:[1,1,1]
	v_cvt_pk_bf16_f32 v232, v181, v2
	ds_write_b16 v108, v232 offset:32976
	ds_read_b128 v[216:219], v2 offset:59232
	s_waitcnt lgkmcnt(13)
	v_pk_fma_f32 v[184:185], v[220:221], v[180:181], v[184:185] op_sel:[0,1,0] op_sel_hi:[1,1,1]
	v_pk_fma_f32 v[186:187], v[222:223], v[180:181], v[186:187] op_sel:[0,1,0] op_sel_hi:[1,1,1]
	ds_read_b128 v[220:223], v2 offset:59248
	s_waitcnt lgkmcnt(13)
	v_pk_fma_f32 v[188:189], v[224:225], v[180:181], v[188:189] op_sel:[0,1,0] op_sel_hi:[1,1,1]
	v_pk_fma_f32 v[190:191], v[226:227], v[180:181], v[190:191] op_sel:[0,1,0] op_sel_hi:[1,1,1]
	ds_read_b128 v[224:227], v2 offset:59296
	s_waitcnt lgkmcnt(13)
	v_pk_fma_f32 v[192:193], v[228:229], v[180:181], v[192:193] op_sel:[0,1,0] op_sel_hi:[1,1,1]
	v_pk_fma_f32 v[194:195], v[230:231], v[180:181], v[194:195] op_sel:[0,1,0] op_sel_hi:[1,1,1]
	ds_read_b128 v[228:231], v2 offset:59312
	s_waitcnt lgkmcnt(13)
	v_pk_fma_f32 v[196:197], v[240:241], v[180:181], v[196:197] op_sel:[0,1,0] op_sel_hi:[1,1,1]
	v_pk_fma_f32 v[198:199], v[242:243], v[180:181], v[198:199] op_sel:[0,1,0] op_sel_hi:[1,1,1]
	ds_read_b128 v[240:243], v2 offset:59328
	s_waitcnt lgkmcnt(12)
	v_pk_fma_f32 v[200:201], v[244:245], v[180:181], v[200:201] op_sel:[0,1,0] op_sel_hi:[1,1,1]
	v_pk_fma_f32 v[202:203], v[246:247], v[180:181], v[202:203] op_sel:[0,1,0] op_sel_hi:[1,1,1]
	ds_read_b128 v[244:247], v2 offset:59344
	s_waitcnt lgkmcnt(12)
	v_pk_fma_f32 v[204:205], v[38:39], v[180:181], v[204:205] op_sel:[0,1,0] op_sel_hi:[1,1,1]
	v_pk_fma_f32 v[206:207], v[40:41], v[180:181], v[206:207] op_sel:[0,1,0] op_sel_hi:[1,1,1]
	ds_read_b128 v[38:41], v2 offset:59360
	s_waitcnt lgkmcnt(12)
	v_pk_fma_f32 v[182:183], v[44:45], v[182:183], v[182:183] op_sel:[0,0,0] op_sel_hi:[1,0,1]
	v_cvt_pk_bf16_f32 v233, v182, v2
	ds_write_b16 v108, v233 offset:33120
	ds_read_b128 v[42:45], v2 offset:59376
	s_waitcnt lgkmcnt(13)
	v_pk_fma_f32 v[184:185], v[46:47], v[182:183], v[184:185] op_sel:[0,0,0] op_sel_hi:[1,0,1]
	v_pk_fma_f32 v[186:187], v[48:49], v[182:183], v[186:187] op_sel:[0,0,0] op_sel_hi:[1,0,1]
	ds_read_b128 v[46:49], v2 offset:59424
	s_waitcnt lgkmcnt(13)
	v_pk_fma_f32 v[188:189], v[50:51], v[182:183], v[188:189] op_sel:[0,0,0] op_sel_hi:[1,0,1]
	v_pk_fma_f32 v[190:191], v[52:53], v[182:183], v[190:191] op_sel:[0,0,0] op_sel_hi:[1,0,1]
	ds_read_b128 v[50:53], v2 offset:59440
	s_waitcnt lgkmcnt(13)
	v_pk_fma_f32 v[192:193], v[208:209], v[182:183], v[192:193] op_sel:[0,0,0] op_sel_hi:[1,0,1]
	v_pk_fma_f32 v[194:195], v[210:211], v[182:183], v[194:195] op_sel:[0,0,0] op_sel_hi:[1,0,1]
	ds_read_b128 v[208:211], v2 offset:59456
	s_waitcnt lgkmcnt(13)
	v_pk_fma_f32 v[196:197], v[212:213], v[182:183], v[196:197] op_sel:[0,0,0] op_sel_hi:[1,0,1]
	v_pk_fma_f32 v[198:199], v[214:215], v[182:183], v[198:199] op_sel:[0,0,0] op_sel_hi:[1,0,1]
	ds_read_b128 v[212:215], v2 offset:59472
	s_waitcnt lgkmcnt(12)
	v_pk_fma_f32 v[200:201], v[216:217], v[182:183], v[200:201] op_sel:[0,0,0] op_sel_hi:[1,0,1]
	v_pk_fma_f32 v[202:203], v[218:219], v[182:183], v[202:203] op_sel:[0,0,0] op_sel_hi:[1,0,1]
	ds_read_b128 v[216:219], v2 offset:59488
	s_waitcnt lgkmcnt(12)
	v_pk_fma_f32 v[204:205], v[220:221], v[182:183], v[204:205] op_sel:[0,0,0] op_sel_hi:[1,0,1]
	v_pk_fma_f32 v[206:207], v[222:223], v[182:183], v[206:207] op_sel:[0,0,0] op_sel_hi:[1,0,1]
	ds_read_b128 v[220:223], v2 offset:59504
	s_waitcnt lgkmcnt(12)
	v_pk_fma_f32 v[184:185], v[224:225], v[182:183], v[184:185] op_sel:[0,1,0] op_sel_hi:[1,1,1]
	v_pk_fma_f32 v[186:187], v[226:227], v[182:183], v[186:187] op_sel:[0,1,0] op_sel_hi:[1,1,1]
	v_cvt_pk_bf16_f32 v248, v183, v2
	ds_write_b16 v108, v248 offset:33264
	ds_read_b128 v[224:227], v2 offset:59552
	s_waitcnt lgkmcnt(13)
	v_pk_fma_f32 v[188:189], v[228:229], v[182:183], v[188:189] op_sel:[0,1,0] op_sel_hi:[1,1,1]
	v_pk_fma_f32 v[190:191], v[230:231], v[182:183], v[190:191] op_sel:[0,1,0] op_sel_hi:[1,1,1]
	ds_read_b128 v[228:231], v2 offset:59568
	s_waitcnt lgkmcnt(13)
	v_pk_fma_f32 v[192:193], v[240:241], v[182:183], v[192:193] op_sel:[0,1,0] op_sel_hi:[1,1,1]
	v_pk_fma_f32 v[194:195], v[242:243], v[182:183], v[194:195] op_sel:[0,1,0] op_sel_hi:[1,1,1]
	ds_read_b128 v[240:243], v2 offset:59584
	s_waitcnt lgkmcnt(13)
	v_pk_fma_f32 v[196:197], v[244:245], v[182:183], v[196:197] op_sel:[0,1,0] op_sel_hi:[1,1,1]
	v_pk_fma_f32 v[198:199], v[246:247], v[182:183], v[198:199] op_sel:[0,1,0] op_sel_hi:[1,1,1]
	ds_read_b128 v[244:247], v2 offset:59600
	s_waitcnt lgkmcnt(13)
	v_pk_fma_f32 v[200:201], v[38:39], v[182:183], v[200:201] op_sel:[0,1,0] op_sel_hi:[1,1,1]
	v_pk_fma_f32 v[202:203], v[40:41], v[182:183], v[202:203] op_sel:[0,1,0] op_sel_hi:[1,1,1]
	ds_read_b128 v[38:41], v2 offset:59616
	s_waitcnt lgkmcnt(12)
	v_pk_fma_f32 v[204:205], v[42:43], v[182:183], v[204:205] op_sel:[0,1,0] op_sel_hi:[1,1,1]
	v_pk_fma_f32 v[206:207], v[44:45], v[182:183], v[206:207] op_sel:[0,1,0] op_sel_hi:[1,1,1]
	ds_read_b128 v[42:45], v2 offset:59632
	s_waitcnt lgkmcnt(12)
	v_pk_fma_f32 v[184:185], v[46:47], v[184:185], v[184:185] op_sel:[0,0,0] op_sel_hi:[1,0,1]
	v_pk_fma_f32 v[186:187], v[48:49], v[184:185], v[186:187] op_sel:[0,0,0] op_sel_hi:[1,0,1]
	v_cvt_pk_bf16_f32 v3, v184, v2
	ds_write_b16 v108, v3 offset:33408
	ds_read_b128 v[46:49], v2 offset:59680
	s_waitcnt lgkmcnt(13)
	v_pk_fma_f32 v[188:189], v[50:51], v[184:185], v[188:189] op_sel:[0,0,0] op_sel_hi:[1,0,1]
	v_pk_fma_f32 v[190:191], v[52:53], v[184:185], v[190:191] op_sel:[0,0,0] op_sel_hi:[1,0,1]
	ds_read_b128 v[50:53], v2 offset:59696
	s_waitcnt lgkmcnt(13)
	v_pk_fma_f32 v[192:193], v[208:209], v[184:185], v[192:193] op_sel:[0,0,0] op_sel_hi:[1,0,1]
	v_pk_fma_f32 v[194:195], v[210:211], v[184:185], v[194:195] op_sel:[0,0,0] op_sel_hi:[1,0,1]
	ds_read_b128 v[208:211], v2 offset:59712
	s_waitcnt lgkmcnt(13)
	v_pk_fma_f32 v[196:197], v[212:213], v[184:185], v[196:197] op_sel:[0,0,0] op_sel_hi:[1,0,1]
	v_pk_fma_f32 v[198:199], v[214:215], v[184:185], v[198:199] op_sel:[0,0,0] op_sel_hi:[1,0,1]
	ds_read_b128 v[212:215], v2 offset:59728
	s_waitcnt lgkmcnt(13)
	v_pk_fma_f32 v[200:201], v[216:217], v[184:185], v[200:201] op_sel:[0,0,0] op_sel_hi:[1,0,1]
	v_pk_fma_f32 v[202:203], v[218:219], v[184:185], v[202:203] op_sel:[0,0,0] op_sel_hi:[1,0,1]
	ds_read_b128 v[216:219], v2 offset:59744
	s_waitcnt lgkmcnt(13)
	v_pk_fma_f32 v[204:205], v[220:221], v[184:185], v[204:205] op_sel:[0,0,0] op_sel_hi:[1,0,1]
	v_pk_fma_f32 v[206:207], v[222:223], v[184:185], v[206:207] op_sel:[0,0,0] op_sel_hi:[1,0,1]
	ds_read_b128 v[220:223], v2 offset:59760
	s_waitcnt lgkmcnt(12)
	v_pk_fma_f32 v[186:187], v[226:227], v[184:185], v[186:187] op_sel:[0,1,0] op_sel_hi:[1,1,1]
	v_cvt_pk_bf16_f32 v232, v185, v2
	ds_write_b16 v108, v232 offset:33552
	ds_read_b128 v[224:227], v2 offset:59824
	s_waitcnt lgkmcnt(13)
	v_pk_fma_f32 v[188:189], v[228:229], v[184:185], v[188:189] op_sel:[0,1,0] op_sel_hi:[1,1,1]
	v_pk_fma_f32 v[190:191], v[230:231], v[184:185], v[190:191] op_sel:[0,1,0] op_sel_hi:[1,1,1]
	ds_read_b128 v[228:231], v2 offset:59840
	s_waitcnt lgkmcnt(13)
	v_pk_fma_f32 v[192:193], v[240:241], v[184:185], v[192:193] op_sel:[0,1,0] op_sel_hi:[1,1,1]
	v_pk_fma_f32 v[194:195], v[242:243], v[184:185], v[194:195] op_sel:[0,1,0] op_sel_hi:[1,1,1]
	ds_read_b128 v[240:243], v2 offset:59856
	s_waitcnt lgkmcnt(13)
	v_pk_fma_f32 v[196:197], v[244:245], v[184:185], v[196:197] op_sel:[0,1,0] op_sel_hi:[1,1,1]
	v_pk_fma_f32 v[198:199], v[246:247], v[184:185], v[198:199] op_sel:[0,1,0] op_sel_hi:[1,1,1]
	ds_read_b128 v[244:247], v2 offset:59872
	s_waitcnt lgkmcnt(13)
	v_pk_fma_f32 v[200:201], v[38:39], v[184:185], v[200:201] op_sel:[0,1,0] op_sel_hi:[1,1,1]
	v_pk_fma_f32 v[202:203], v[40:41], v[184:185], v[202:203] op_sel:[0,1,0] op_sel_hi:[1,1,1]
	ds_read_b128 v[38:41], v2 offset:59888
	s_waitcnt lgkmcnt(13)
	v_pk_fma_f32 v[204:205], v[42:43], v[184:185], v[204:205] op_sel:[0,1,0] op_sel_hi:[1,1,1]
	v_pk_fma_f32 v[206:207], v[44:45], v[184:185], v[206:207] op_sel:[0,1,0] op_sel_hi:[1,1,1]
	ds_read_b128 v[42:45], v2 offset:59952
	s_waitcnt lgkmcnt(12)
	v_pk_fma_f32 v[186:187], v[48:49], v[186:187], v[186:187] op_sel:[0,0,0] op_sel_hi:[1,0,1]
	v_cvt_pk_bf16_f32 v233, v186, v2
	ds_write_b16 v108, v233 offset:33696
	ds_read_b128 v[46:49], v2 offset:59968
	s_waitcnt lgkmcnt(13)
	v_pk_fma_f32 v[188:189], v[50:51], v[186:187], v[188:189] op_sel:[0,0,0] op_sel_hi:[1,0,1]
	v_pk_fma_f32 v[190:191], v[52:53], v[186:187], v[190:191] op_sel:[0,0,0] op_sel_hi:[1,0,1]
	ds_read_b128 v[50:53], v2 offset:59984
	s_waitcnt lgkmcnt(13)
	v_pk_fma_f32 v[192:193], v[208:209], v[186:187], v[192:193] op_sel:[0,0,0] op_sel_hi:[1,0,1]
	v_pk_fma_f32 v[194:195], v[210:211], v[186:187], v[194:195] op_sel:[0,0,0] op_sel_hi:[1,0,1]
	ds_read_b128 v[208:211], v2 offset:60000
	s_waitcnt lgkmcnt(13)
	v_pk_fma_f32 v[196:197], v[212:213], v[186:187], v[196:197] op_sel:[0,0,0] op_sel_hi:[1,0,1]
	v_pk_fma_f32 v[198:199], v[214:215], v[186:187], v[198:199] op_sel:[0,0,0] op_sel_hi:[1,0,1]
	ds_read_b128 v[212:215], v2 offset:60016
	s_waitcnt lgkmcnt(13)
	v_pk_fma_f32 v[200:201], v[216:217], v[186:187], v[200:201] op_sel:[0,0,0] op_sel_hi:[1,0,1]
	v_pk_fma_f32 v[202:203], v[218:219], v[186:187], v[202:203] op_sel:[0,0,0] op_sel_hi:[1,0,1]
	ds_read_b128 v[216:219], v2 offset:60080
	s_waitcnt lgkmcnt(13)
	v_pk_fma_f32 v[204:205], v[220:221], v[186:187], v[204:205] op_sel:[0,0,0] op_sel_hi:[1,0,1]
	v_pk_fma_f32 v[206:207], v[222:223], v[186:187], v[206:207] op_sel:[0,0,0] op_sel_hi:[1,0,1]
	ds_read_b128 v[220:223], v2 offset:60096
	s_waitcnt lgkmcnt(12)
	v_pk_fma_f32 v[188:189], v[224:225], v[186:187], v[188:189] op_sel:[0,1,0] op_sel_hi:[1,1,1]
	v_pk_fma_f32 v[190:191], v[226:227], v[186:187], v[190:191] op_sel:[0,1,0] op_sel_hi:[1,1,1]
	v_cvt_pk_bf16_f32 v248, v187, v2
	ds_write_b16 v108, v248 offset:33840
	ds_read_b128 v[224:227], v2 offset:60112
	s_waitcnt lgkmcnt(13)
	v_pk_fma_f32 v[192:193], v[228:229], v[186:187], v[192:193] op_sel:[0,1,0] op_sel_hi:[1,1,1]
	v_pk_fma_f32 v[194:195], v[230:231], v[186:187], v[194:195] op_sel:[0,1,0] op_sel_hi:[1,1,1]
	ds_read_b128 v[228:231], v2 offset:60128
	s_waitcnt lgkmcnt(13)
	v_pk_fma_f32 v[196:197], v[240:241], v[186:187], v[196:197] op_sel:[0,1,0] op_sel_hi:[1,1,1]
	v_pk_fma_f32 v[198:199], v[242:243], v[186:187], v[198:199] op_sel:[0,1,0] op_sel_hi:[1,1,1]
	ds_read_b128 v[240:243], v2 offset:60144
	s_waitcnt lgkmcnt(13)
	v_pk_fma_f32 v[200:201], v[244:245], v[186:187], v[200:201] op_sel:[0,1,0] op_sel_hi:[1,1,1]
	v_pk_fma_f32 v[202:203], v[246:247], v[186:187], v[202:203] op_sel:[0,1,0] op_sel_hi:[1,1,1]
	ds_read_b128 v[244:247], v2 offset:60208
	s_waitcnt lgkmcnt(13)
	v_pk_fma_f32 v[204:205], v[38:39], v[186:187], v[204:205] op_sel:[0,1,0] op_sel_hi:[1,1,1]
	v_pk_fma_f32 v[206:207], v[40:41], v[186:187], v[206:207] op_sel:[0,1,0] op_sel_hi:[1,1,1]
	ds_read_b128 v[38:41], v2 offset:60224
	s_waitcnt lgkmcnt(13)
	v_pk_fma_f32 v[188:189], v[42:43], v[188:189], v[188:189] op_sel:[0,0,0] op_sel_hi:[1,0,1]
	v_pk_fma_f32 v[190:191], v[44:45], v[188:189], v[190:191] op_sel:[0,0,0] op_sel_hi:[1,0,1]
	v_cvt_pk_bf16_f32 v3, v188, v2
	ds_write_b16 v108, v3 offset:33984
	ds_read_b128 v[42:45], v2 offset:60240
	s_waitcnt lgkmcnt(13)
	v_pk_fma_f32 v[192:193], v[46:47], v[188:189], v[192:193] op_sel:[0,0,0] op_sel_hi:[1,0,1]
	v_pk_fma_f32 v[194:195], v[48:49], v[188:189], v[194:195] op_sel:[0,0,0] op_sel_hi:[1,0,1]
	ds_read_b128 v[46:49], v2 offset:60256
	s_waitcnt lgkmcnt(13)
	v_pk_fma_f32 v[196:197], v[50:51], v[188:189], v[196:197] op_sel:[0,0,0] op_sel_hi:[1,0,1]
	v_pk_fma_f32 v[198:199], v[52:53], v[188:189], v[198:199] op_sel:[0,0,0] op_sel_hi:[1,0,1]
	ds_read_b128 v[50:53], v2 offset:60272
	s_waitcnt lgkmcnt(13)
	v_pk_fma_f32 v[200:201], v[208:209], v[188:189], v[200:201] op_sel:[0,0,0] op_sel_hi:[1,0,1]
	v_pk_fma_f32 v[202:203], v[210:211], v[188:189], v[202:203] op_sel:[0,0,0] op_sel_hi:[1,0,1]
	ds_read_b128 v[208:211], v2 offset:60352
	s_waitcnt lgkmcnt(13)
	v_pk_fma_f32 v[204:205], v[212:213], v[188:189], v[204:205] op_sel:[0,0,0] op_sel_hi:[1,0,1]
	v_pk_fma_f32 v[206:207], v[214:215], v[188:189], v[206:207] op_sel:[0,0,0] op_sel_hi:[1,0,1]
	ds_read_b128 v[212:215], v2 offset:60368
	s_waitcnt lgkmcnt(13)
	v_pk_fma_f32 v[190:191], v[218:219], v[188:189], v[190:191] op_sel:[0,1,0] op_sel_hi:[1,1,1]
	v_cvt_pk_bf16_f32 v232, v189, v2
	ds_write_b16 v108, v232 offset:34128
	ds_read_b128 v[216:219], v2 offset:60384
	s_waitcnt lgkmcnt(14)
	v_pk_fma_f32 v[192:193], v[220:221], v[188:189], v[192:193] op_sel:[0,1,0] op_sel_hi:[1,1,1]
	v_pk_fma_f32 v[194:195], v[222:223], v[188:189], v[194:195] op_sel:[0,1,0] op_sel_hi:[1,1,1]
	ds_read_b128 v[220:223], v2 offset:60400
	s_waitcnt lgkmcnt(13)
	v_pk_fma_f32 v[196:197], v[224:225], v[188:189], v[196:197] op_sel:[0,1,0] op_sel_hi:[1,1,1]
	v_pk_fma_f32 v[198:199], v[226:227], v[188:189], v[198:199] op_sel:[0,1,0] op_sel_hi:[1,1,1]
	ds_read_b128 v[224:227], v2 offset:60480
	s_waitcnt lgkmcnt(13)
	v_pk_fma_f32 v[200:201], v[228:229], v[188:189], v[200:201] op_sel:[0,1,0] op_sel_hi:[1,1,1]
	v_pk_fma_f32 v[202:203], v[230:231], v[188:189], v[202:203] op_sel:[0,1,0] op_sel_hi:[1,1,1]
	ds_read_b128 v[228:231], v2 offset:60496
	s_waitcnt lgkmcnt(13)
	v_pk_fma_f32 v[204:205], v[240:241], v[188:189], v[204:205] op_sel:[0,1,0] op_sel_hi:[1,1,1]
	v_pk_fma_f32 v[206:207], v[242:243], v[188:189], v[206:207] op_sel:[0,1,0] op_sel_hi:[1,1,1]
	ds_read_b128 v[240:243], v2 offset:60512
	s_waitcnt lgkmcnt(13)
	v_pk_fma_f32 v[190:191], v[246:247], v[190:191], v[190:191] op_sel:[0,0,0] op_sel_hi:[1,0,1]
	v_cvt_pk_bf16_f32 v233, v190, v2
	ds_write_b16 v108, v233 offset:34272
	ds_read_b128 v[244:247], v2 offset:60528
	s_waitcnt lgkmcnt(14)
	v_pk_fma_f32 v[192:193], v[38:39], v[190:191], v[192:193] op_sel:[0,0,0] op_sel_hi:[1,0,1]
	v_pk_fma_f32 v[194:195], v[40:41], v[190:191], v[194:195] op_sel:[0,0,0] op_sel_hi:[1,0,1]
	ds_read_b128 v[38:41], v2 offset:60608
	s_waitcnt lgkmcnt(13)
	v_pk_fma_f32 v[196:197], v[42:43], v[190:191], v[196:197] op_sel:[0,0,0] op_sel_hi:[1,0,1]
	v_pk_fma_f32 v[198:199], v[44:45], v[190:191], v[198:199] op_sel:[0,0,0] op_sel_hi:[1,0,1]
	ds_read_b128 v[42:45], v2 offset:60624
	s_waitcnt lgkmcnt(13)
	v_pk_fma_f32 v[200:201], v[46:47], v[190:191], v[200:201] op_sel:[0,0,0] op_sel_hi:[1,0,1]
	v_pk_fma_f32 v[202:203], v[48:49], v[190:191], v[202:203] op_sel:[0,0,0] op_sel_hi:[1,0,1]
	ds_read_b128 v[46:49], v2 offset:60640
	s_waitcnt lgkmcnt(13)
	v_pk_fma_f32 v[204:205], v[50:51], v[190:191], v[204:205] op_sel:[0,0,0] op_sel_hi:[1,0,1]
	v_pk_fma_f32 v[206:207], v[52:53], v[190:191], v[206:207] op_sel:[0,0,0] op_sel_hi:[1,0,1]
	ds_read_b128 v[50:53], v2 offset:60656
	s_waitcnt lgkmcnt(13)
	v_pk_fma_f32 v[192:193], v[208:209], v[190:191], v[192:193] op_sel:[0,1,0] op_sel_hi:[1,1,1]
	v_pk_fma_f32 v[194:195], v[210:211], v[190:191], v[194:195] op_sel:[0,1,0] op_sel_hi:[1,1,1]
	v_cvt_pk_bf16_f32 v248, v191, v2
	ds_write_b16 v108, v248 offset:34416
	ds_read_b128 v[208:211], v2 offset:60736
	s_waitcnt lgkmcnt(14)
	v_pk_fma_f32 v[196:197], v[212:213], v[190:191], v[196:197] op_sel:[0,1,0] op_sel_hi:[1,1,1]
	v_pk_fma_f32 v[198:199], v[214:215], v[190:191], v[198:199] op_sel:[0,1,0] op_sel_hi:[1,1,1]
	ds_read_b128 v[212:215], v2 offset:60752
	s_waitcnt lgkmcnt(13)
	v_pk_fma_f32 v[200:201], v[216:217], v[190:191], v[200:201] op_sel:[0,1,0] op_sel_hi:[1,1,1]
	v_pk_fma_f32 v[202:203], v[218:219], v[190:191], v[202:203] op_sel:[0,1,0] op_sel_hi:[1,1,1]
	ds_read_b128 v[216:219], v2 offset:60768
	s_waitcnt lgkmcnt(13)
	v_pk_fma_f32 v[204:205], v[220:221], v[190:191], v[204:205] op_sel:[0,1,0] op_sel_hi:[1,1,1]
	v_pk_fma_f32 v[206:207], v[222:223], v[190:191], v[206:207] op_sel:[0,1,0] op_sel_hi:[1,1,1]
	ds_read_b128 v[220:223], v2 offset:60784
	s_waitcnt lgkmcnt(13)
	v_pk_fma_f32 v[192:193], v[224:225], v[192:193], v[192:193] op_sel:[0,0,0] op_sel_hi:[1,0,1]
	v_pk_fma_f32 v[194:195], v[226:227], v[192:193], v[194:195] op_sel:[0,0,0] op_sel_hi:[1,0,1]
	v_cvt_pk_bf16_f32 v3, v192, v2
	ds_write_b16 v108, v3 offset:34560
	ds_read_b128 v[224:227], v2 offset:60880
	s_waitcnt lgkmcnt(14)
	v_pk_fma_f32 v[196:197], v[228:229], v[192:193], v[196:197] op_sel:[0,0,0] op_sel_hi:[1,0,1]
	v_pk_fma_f32 v[198:199], v[230:231], v[192:193], v[198:199] op_sel:[0,0,0] op_sel_hi:[1,0,1]
	ds_read_b128 v[228:231], v2 offset:60896
	s_waitcnt lgkmcnt(14)
	v_pk_fma_f32 v[200:201], v[240:241], v[192:193], v[200:201] op_sel:[0,0,0] op_sel_hi:[1,0,1]
	v_pk_fma_f32 v[202:203], v[242:243], v[192:193], v[202:203] op_sel:[0,0,0] op_sel_hi:[1,0,1]
	ds_read_b128 v[240:243], v2 offset:60912
	s_waitcnt lgkmcnt(13)
	v_pk_fma_f32 v[204:205], v[244:245], v[192:193], v[204:205] op_sel:[0,0,0] op_sel_hi:[1,0,1]
	v_pk_fma_f32 v[206:207], v[246:247], v[192:193], v[206:207] op_sel:[0,0,0] op_sel_hi:[1,0,1]
	ds_read_b128 v[244:247], v2 offset:61008
	s_waitcnt lgkmcnt(13)
	v_pk_fma_f32 v[194:195], v[40:41], v[192:193], v[194:195] op_sel:[0,1,0] op_sel_hi:[1,1,1]
	v_cvt_pk_bf16_f32 v232, v193, v2
	ds_write_b16 v108, v232 offset:34704
	ds_read_b128 v[38:41], v2 offset:61024
	s_waitcnt lgkmcnt(14)
	v_pk_fma_f32 v[196:197], v[42:43], v[192:193], v[196:197] op_sel:[0,1,0] op_sel_hi:[1,1,1]
	v_pk_fma_f32 v[198:199], v[44:45], v[192:193], v[198:199] op_sel:[0,1,0] op_sel_hi:[1,1,1]
	ds_read_b128 v[42:45], v2 offset:61040
	s_waitcnt lgkmcnt(14)
	v_pk_fma_f32 v[200:201], v[46:47], v[192:193], v[200:201] op_sel:[0,1,0] op_sel_hi:[1,1,1]
	v_pk_fma_f32 v[202:203], v[48:49], v[192:193], v[202:203] op_sel:[0,1,0] op_sel_hi:[1,1,1]
	ds_read_b128 v[46:49], v2 offset:61136
	s_waitcnt lgkmcnt(14)
	v_pk_fma_f32 v[204:205], v[50:51], v[192:193], v[204:205] op_sel:[0,1,0] op_sel_hi:[1,1,1]
	v_pk_fma_f32 v[206:207], v[52:53], v[192:193], v[206:207] op_sel:[0,1,0] op_sel_hi:[1,1,1]
	ds_read_b128 v[50:53], v2 offset:61152
	s_waitcnt lgkmcnt(13)
	v_pk_fma_f32 v[194:195], v[210:211], v[194:195], v[194:195] op_sel:[0,0,0] op_sel_hi:[1,0,1]
	v_cvt_pk_bf16_f32 v233, v194, v2
	ds_write_b16 v108, v233 offset:34848
	ds_read_b128 v[208:211], v2 offset:61168
	s_waitcnt lgkmcnt(14)
	v_pk_fma_f32 v[196:197], v[212:213], v[194:195], v[196:197] op_sel:[0,0,0] op_sel_hi:[1,0,1]
	v_pk_fma_f32 v[198:199], v[214:215], v[194:195], v[198:199] op_sel:[0,0,0] op_sel_hi:[1,0,1]
	ds_read_b128 v[212:215], v2 offset:61264
	s_waitcnt lgkmcnt(14)
	v_pk_fma_f32 v[200:201], v[216:217], v[194:195], v[200:201] op_sel:[0,0,0] op_sel_hi:[1,0,1]
	v_pk_fma_f32 v[202:203], v[218:219], v[194:195], v[202:203] op_sel:[0,0,0] op_sel_hi:[1,0,1]
	ds_read_b128 v[216:219], v2 offset:61280
	s_waitcnt lgkmcnt(14)
	v_pk_fma_f32 v[204:205], v[220:221], v[194:195], v[204:205] op_sel:[0,0,0] op_sel_hi:[1,0,1]
	v_pk_fma_f32 v[206:207], v[222:223], v[194:195], v[206:207] op_sel:[0,0,0] op_sel_hi:[1,0,1]
	ds_read_b128 v[220:223], v2 offset:61296
	s_waitcnt lgkmcnt(13)
	v_pk_fma_f32 v[196:197], v[224:225], v[194:195], v[196:197] op_sel:[0,1,0] op_sel_hi:[1,1,1]
	v_pk_fma_f32 v[198:199], v[226:227], v[194:195], v[198:199] op_sel:[0,1,0] op_sel_hi:[1,1,1]
	v_cvt_pk_bf16_f32 v248, v195, v2
	ds_write_b16 v108, v248 offset:34992
	ds_read_b128 v[224:227], v2 offset:61408
	s_waitcnt lgkmcnt(14)
	v_pk_fma_f32 v[200:201], v[228:229], v[194:195], v[200:201] op_sel:[0,1,0] op_sel_hi:[1,1,1]
	v_pk_fma_f32 v[202:203], v[230:231], v[194:195], v[202:203] op_sel:[0,1,0] op_sel_hi:[1,1,1]
	ds_read_b128 v[228:231], v2 offset:61424
	s_waitcnt lgkmcnt(14)
	v_pk_fma_f32 v[204:205], v[240:241], v[194:195], v[204:205] op_sel:[0,1,0] op_sel_hi:[1,1,1]
	v_pk_fma_f32 v[206:207], v[242:243], v[194:195], v[206:207] op_sel:[0,1,0] op_sel_hi:[1,1,1]
	ds_read_b128 v[240:243], v2 offset:61536
	s_waitcnt lgkmcnt(14)
	v_pk_fma_f32 v[196:197], v[244:245], v[196:197], v[196:197] op_sel:[0,0,0] op_sel_hi:[1,0,1]
	v_pk_fma_f32 v[198:199], v[246:247], v[196:197], v[198:199] op_sel:[0,0,0] op_sel_hi:[1,0,1]
	v_cvt_pk_bf16_f32 v3, v196, v2
	ds_write_b16 v108, v3 offset:35136
	s_waitcnt lgkmcnt(14)
	ds_read_b128 v[244:247], v2 offset:61552
	s_waitcnt lgkmcnt(14)
	v_pk_fma_f32 v[200:201], v[38:39], v[196:197], v[200:201] op_sel:[0,0,0] op_sel_hi:[1,0,1]
	v_pk_fma_f32 v[202:203], v[40:41], v[196:197], v[202:203] op_sel:[0,0,0] op_sel_hi:[1,0,1]
	ds_read_b128 v[38:41], v2 offset:61664
	s_waitcnt lgkmcnt(14)
	v_pk_fma_f32 v[204:205], v[42:43], v[196:197], v[204:205] op_sel:[0,0,0] op_sel_hi:[1,0,1]
	v_pk_fma_f32 v[206:207], v[44:45], v[196:197], v[206:207] op_sel:[0,0,0] op_sel_hi:[1,0,1]
	ds_read_b128 v[42:45], v2 offset:61680
	s_waitcnt lgkmcnt(14)
	v_pk_fma_f32 v[198:199], v[48:49], v[196:197], v[198:199] op_sel:[0,1,0] op_sel_hi:[1,1,1]
	v_cvt_pk_bf16_f32 v232, v197, v2
	ds_write_b16 v108, v232 offset:35280
	s_waitcnt lgkmcnt(14)
	ds_read_b128 v[46:49], v2 offset:61792
	v_pk_fma_f32 v[200:201], v[50:51], v[196:197], v[200:201] op_sel:[0,1,0] op_sel_hi:[1,1,1]
	v_pk_fma_f32 v[202:203], v[52:53], v[196:197], v[202:203] op_sel:[0,1,0] op_sel_hi:[1,1,1]
	s_waitcnt lgkmcnt(14)
	ds_read_b128 v[50:53], v2 offset:61808
	s_waitcnt lgkmcnt(14)
	v_pk_fma_f32 v[204:205], v[208:209], v[196:197], v[204:205] op_sel:[0,1,0] op_sel_hi:[1,1,1]
	v_pk_fma_f32 v[206:207], v[210:211], v[196:197], v[206:207] op_sel:[0,1,0] op_sel_hi:[1,1,1]
	ds_read_b128 v[208:211], v2 offset:61936
	s_waitcnt lgkmcnt(14)
	v_pk_fma_f32 v[198:199], v[214:215], v[198:199], v[198:199] op_sel:[0,0,0] op_sel_hi:[1,0,1]
	v_cvt_pk_bf16_f32 v233, v198, v2
	ds_write_b16 v108, v233 offset:35424
	s_waitcnt lgkmcnt(14)
	ds_read_b128 v[212:215], v2 offset:62064
	v_pk_fma_f32 v[200:201], v[216:217], v[198:199], v[200:201] op_sel:[0,0,0] op_sel_hi:[1,0,1]
	v_pk_fma_f32 v[202:203], v[218:219], v[198:199], v[202:203] op_sel:[0,0,0] op_sel_hi:[1,0,1]
	s_waitcnt lgkmcnt(14)
	ds_read_b128 v[216:219], v2 offset:62192
	v_pk_fma_f32 v[204:205], v[220:221], v[198:199], v[204:205] op_sel:[0,0,0] op_sel_hi:[1,0,1]
	v_pk_fma_f32 v[206:207], v[222:223], v[198:199], v[206:207] op_sel:[0,0,0] op_sel_hi:[1,0,1]
	s_waitcnt lgkmcnt(14)
	ds_read_b128 v[220:223], v2 offset:62320
	s_waitcnt lgkmcnt(14)
	v_pk_fma_f32 v[200:201], v[224:225], v[198:199], v[200:201] op_sel:[0,1,0] op_sel_hi:[1,1,1]
	v_pk_fma_f32 v[202:203], v[226:227], v[198:199], v[202:203] op_sel:[0,1,0] op_sel_hi:[1,1,1]
	v_cvt_pk_bf16_f32 v248, v199, v2
	ds_write_b16 v108, v248 offset:35568
	s_waitcnt lgkmcnt(14)
	v_pk_fma_f32 v[204:205], v[228:229], v[198:199], v[204:205] op_sel:[0,1,0] op_sel_hi:[1,1,1]
	v_pk_fma_f32 v[206:207], v[230:231], v[198:199], v[206:207] op_sel:[0,1,0] op_sel_hi:[1,1,1]
	s_waitcnt lgkmcnt(13)
	v_pk_fma_f32 v[200:201], v[240:241], v[200:201], v[200:201] op_sel:[0,0,0] op_sel_hi:[1,0,1]
	v_pk_fma_f32 v[202:203], v[242:243], v[200:201], v[202:203] op_sel:[0,0,0] op_sel_hi:[1,0,1]
	v_cvt_pk_bf16_f32 v3, v200, v2
	ds_write_b16 v108, v3 offset:35712
	s_waitcnt lgkmcnt(12)
	v_pk_fma_f32 v[204:205], v[244:245], v[200:201], v[204:205] op_sel:[0,0,0] op_sel_hi:[1,0,1]
	v_pk_fma_f32 v[206:207], v[246:247], v[200:201], v[206:207] op_sel:[0,0,0] op_sel_hi:[1,0,1]
	s_waitcnt lgkmcnt(11)
	v_pk_fma_f32 v[202:203], v[40:41], v[200:201], v[202:203] op_sel:[0,1,0] op_sel_hi:[1,1,1]
	v_cvt_pk_bf16_f32 v232, v201, v2
	ds_write_b16 v108, v232 offset:35856
	s_waitcnt lgkmcnt(11)
	v_pk_fma_f32 v[204:205], v[42:43], v[200:201], v[204:205] op_sel:[0,1,0] op_sel_hi:[1,1,1]
	v_pk_fma_f32 v[206:207], v[44:45], v[200:201], v[206:207] op_sel:[0,1,0] op_sel_hi:[1,1,1]
	s_waitcnt lgkmcnt(9)
	v_pk_fma_f32 v[202:203], v[48:49], v[202:203], v[202:203] op_sel:[0,0,0] op_sel_hi:[1,0,1]
	v_cvt_pk_bf16_f32 v233, v202, v2
	ds_write_b16 v108, v233 offset:36000
	s_waitcnt lgkmcnt(9)
	v_pk_fma_f32 v[204:205], v[50:51], v[202:203], v[204:205] op_sel:[0,0,0] op_sel_hi:[1,0,1]
	v_pk_fma_f32 v[206:207], v[52:53], v[202:203], v[206:207] op_sel:[0,0,0] op_sel_hi:[1,0,1]
	s_waitcnt lgkmcnt(8)
	v_pk_fma_f32 v[204:205], v[208:209], v[202:203], v[204:205] op_sel:[0,1,0] op_sel_hi:[1,1,1]
	v_pk_fma_f32 v[206:207], v[210:211], v[202:203], v[206:207] op_sel:[0,1,0] op_sel_hi:[1,1,1]
	v_cvt_pk_bf16_f32 v248, v203, v2
	ds_write_b16 v108, v248 offset:36144
	s_waitcnt lgkmcnt(7)
	v_pk_fma_f32 v[204:205], v[212:213], v[204:205], v[204:205] op_sel:[0,0,0] op_sel_hi:[1,0,1]
	v_pk_fma_f32 v[206:207], v[214:215], v[204:205], v[206:207] op_sel:[0,0,0] op_sel_hi:[1,0,1]
	v_cvt_pk_bf16_f32 v3, v204, v2
	ds_write_b16 v108, v3 offset:36288
	s_waitcnt lgkmcnt(7)
	v_pk_fma_f32 v[206:207], v[218:219], v[204:205], v[206:207] op_sel:[0,1,0] op_sel_hi:[1,1,1]
	v_cvt_pk_bf16_f32 v232, v205, v2
	ds_write_b16 v108, v232 offset:36432
	s_waitcnt lgkmcnt(7)
	v_pk_fma_f32 v[206:207], v[222:223], v[206:207], v[206:207] op_sel:[0,0,0] op_sel_hi:[1,0,1]
	v_cvt_pk_bf16_f32 v233, v206, v2
	ds_write_b16 v108, v233 offset:36576
	v_cvt_pk_bf16_f32 v248, v207, v2
	ds_write_b16 v108, v248 offset:36720

.LBB0_3366:
	s_cmp_eq_u32 s25, 0
	s_cselect_b64 s[34:35], -1, 0
	s_or_b64 s[34:35], s[8:9], s[34:35]
	s_and_b64 vcc, exec, s[34:35]
	s_waitcnt lgkmcnt(0)
	s_barrier
	s_cbranch_vccnz .LBB0_3369
	v_cndmask_b32_e64 v3, 0, 1, s[62:63]
	s_add_i32 s25, s25, -1
	v_lshlrev_b32_e32 v3, 7, v3
	v_readlane_b32 s34, v252, 12
	s_bitcmp0_b32 s25, 0
	s_movk_i32 s25, 0x6c00
	v_add_u32_e32 v3, s34, v3
	s_cselect_b32 s25, s25, 0x13600
	s_cselect_b32 s34, s20, 0x14800
	v_add_u32_e32 v4, s34, v122
	v_add_u32_e32 v5, s25, v122
	v_mov_b32_e32 v38, v123
	s_mov_b32 s25, s39
	ds_read_b32 v208, v38
	ds_read_b32 v209, v3
	ds_read_u16 v210, v5
	ds_read_u16 v211, v4
.LBB0_3368:
	s_waitcnt lgkmcnt(0)
	v_mov_b32_e32 v39, v208
	v_mov_b32_e32 v86, v209
	v_mov_b32_e32 v212, v210
	v_mov_b32_e32 v213, v211
	v_add_u32_e32 v38, 0x700, v38
	v_add_u32_e32 v3, 28, v3
	v_add_u32_e32 v5, 0x3f0, v5
	v_add_u32_e32 v4, 0x3f0, v4
	ds_read_b32 v208, v38
	ds_read_b32 v209, v3
	ds_read_u16 v210, v5
	ds_read_u16 v211, v4
	v_add_f32_dpp v40, v39, v39 quad_perm:[1,0,3,2] row_mask:0xf bank_mask:0xf bound_ctrl:1
	s_nop 1
	v_add_f32_dpp v40, v40, v40 quad_perm:[2,3,0,1] row_mask:0xf bank_mask:0xf bound_ctrl:1
	s_nop 1
	v_add_f32_dpp v40, v40, v40 row_ror:4 row_mask:0xf bank_mask:0xf bound_ctrl:1
	s_nop 1
	v_add_f32_dpp v40, v40, v40 row_ror:8 row_mask:0xf bank_mask:0xf bound_ctrl:1
	s_nop 0
	v_readlane_b32 s64, v40, 16
	v_readlane_b32 s65, v40, 48
	v_readlane_b32 s34, v40, 0
	v_readlane_b32 s35, v40, 32
	v_mov_b32_e32 v40, s64
	v_mov_b32_e32 v41, s65
	v_pk_add_f32 v[40:41], s[34:35], v[40:41]
	s_nop 0
	v_add_f32_e32 v40, v40, v41
	v_fmac_f32_e32 v39, 0xbc800000, v40
	v_mul_f32_e32 v40, v39, v39
	s_nop 1
	v_mov_b32_dpp v40, v40 quad_perm:[1,0,3,2] row_mask:0xf bank_mask:0xf bound_ctrl:1
	v_fmac_f32_e32 v40, v39, v39
	s_nop 1
	v_add_f32_dpp v40, v40, v40 quad_perm:[2,3,0,1] row_mask:0xf bank_mask:0xf bound_ctrl:1
	s_nop 1
	v_add_f32_dpp v40, v40, v40 row_ror:4 row_mask:0xf bank_mask:0xf bound_ctrl:1
	s_nop 1
	v_add_f32_dpp v40, v40, v40 row_ror:8 row_mask:0xf bank_mask:0xf bound_ctrl:1
	s_nop 0
	v_readlane_b32 s64, v40, 16
	v_readlane_b32 s65, v40, 48
	v_readlane_b32 s34, v40, 0
	v_readlane_b32 s35, v40, 32
	v_mov_b32_e32 v40, s64
	v_mov_b32_e32 v41, s65
	v_pk_add_f32 v[40:41], s[34:35], v[40:41]
	s_add_i32 s34, s22, s25
	v_add_f32_e32 v40, v40, v41
	v_fmamk_f32 v40, v40, 0x3c800000, v130
	v_rsq_f32_e32 v40, v40
	s_ashr_i32 s35, s34, 31
	s_lshl_b64 s[34:35], s[34:35], 11
	v_mul_f32_e32 v41, v39, v40
	v_lshlrev_b32_e32 v40, 16, v212
	v_pk_mul_f32 v[40:41], v[86:87], v[40:41]
	s_nop 0
	v_add_f32_e32 v39, v85, v41
	v_add_f32_e32 v39, v40, v39
	v_lshlrev_b32_e32 v40, 16, v213
	v_mul_f32_e32 v39, v39, v40
	v_lshl_add_u64 v[40:41], v[88:89], 0, s[34:35]
	s_add_i32 s34, s25, 7
	s_add_i32 s25, s25, -1
	s_cmp_lt_i32 s25, 25
	s_mov_b32 s25, s34
	v_cvt_pk_bf16_f32 v39, v39, v2
	global_store_short v[40:41], v39, off
	s_cbranch_scc1 .LBB0_3368
.LBB0_3369:
	s_and_b64 vcc, exec, s[30:31]
	s_cbranch_vccnz .LBB0_3371
	ds_read2st64_b32 v[176:177], v111 offset0:244 offset1:245
	ds_read2st64_b32 v[178:179], v111 offset0:246 offset1:247
	ds_read2st64_b32 v[180:181], v111 offset0:248 offset1:249
	ds_read2st64_b32 v[182:183], v111 offset0:250 offset1:251
	ds_read2st64_b32 v[184:185], v111 offset0:252 offset1:253
	ds_read2st64_b32 v[186:187], v111 offset0:254 offset1:255
	ds_read2st64_b32 v[188:189], v112 offset0:12 offset1:13
	ds_read2st64_b32 v[190:191], v112 offset0:14 offset1:15
	ds_read2st64_b32 v[192:193], v112 offset0:16 offset1:17
	ds_read2st64_b32 v[194:195], v112 offset0:18 offset1:19
	ds_read2st64_b32 v[196:197], v112 offset0:20 offset1:21
	ds_read2st64_b32 v[198:199], v112 offset0:22 offset1:23
	ds_read2st64_b32 v[200:201], v112 offset0:24 offset1:25
	ds_read2st64_b32 v[202:203], v112 offset0:26 offset1:27
	ds_read2st64_b32 v[204:205], v112 offset0:28 offset1:29
	s_waitcnt lgkmcnt(14)
	ds_read2st64_b32 v[206:207], v112 offset0:30 offset1:31
	s_waitcnt lgkmcnt(14)
	ds_read_b128 v[208:211], v2 offset:58368
	s_waitcnt lgkmcnt(14)
	ds_read_b128 v[212:215], v2 offset:58384
	s_waitcnt lgkmcnt(14)
	ds_read_b128 v[216:219], v2 offset:58400
	s_waitcnt lgkmcnt(14)
	ds_read_b128 v[220:223], v2 offset:58416
	s_waitcnt lgkmcnt(14)
	ds_read_b128 v[224:227], v2 offset:58432
	s_waitcnt lgkmcnt(14)
	ds_read_b128 v[228:231], v2 offset:58448
	s_waitcnt lgkmcnt(14)
	ds_read_b128 v[240:243], v2 offset:58464
	s_waitcnt lgkmcnt(14)
	ds_read_b128 v[244:247], v2 offset:58480
	s_waitcnt lgkmcnt(14)
	ds_read_b128 v[38:41], v2 offset:58496
	s_waitcnt lgkmcnt(14)
	ds_read_b128 v[42:45], v2 offset:58512
	s_waitcnt lgkmcnt(14)
	ds_read_b128 v[46:49], v2 offset:58528
	s_waitcnt lgkmcnt(14)
	ds_read_b128 v[50:53], v2 offset:58544
	s_waitcnt lgkmcnt(11)
	v_pk_fma_f32 v[176:177], v[208:209], v[176:177], v[176:177] op_sel:[0,0,0] op_sel_hi:[1,0,1]
	v_pk_fma_f32 v[178:179], v[210:211], v[176:177], v[178:179] op_sel:[0,0,0] op_sel_hi:[1,0,1]
	v_cvt_pk_bf16_f32 v3, v176, v2
	ds_write_b16 v113, v3 offset:32256
	ds_read_b128 v[208:211], v2 offset:58560
	s_waitcnt lgkmcnt(12)
	v_pk_fma_f32 v[180:181], v[212:213], v[176:177], v[180:181] op_sel:[0,0,0] op_sel_hi:[1,0,1]
	v_pk_fma_f32 v[182:183], v[214:215], v[176:177], v[182:183] op_sel:[0,0,0] op_sel_hi:[1,0,1]
	ds_read_b128 v[212:215], v2 offset:58576
	s_waitcnt lgkmcnt(12)
	v_pk_fma_f32 v[184:185], v[216:217], v[176:177], v[184:185] op_sel:[0,0,0] op_sel_hi:[1,0,1]
	v_pk_fma_f32 v[186:187], v[218:219], v[176:177], v[186:187] op_sel:[0,0,0] op_sel_hi:[1,0,1]
	ds_read_b128 v[216:219], v2 offset:58592
	s_waitcnt lgkmcnt(12)
	v_pk_fma_f32 v[188:189], v[220:221], v[176:177], v[188:189] op_sel:[0,0,0] op_sel_hi:[1,0,1]
	v_pk_fma_f32 v[190:191], v[222:223], v[176:177], v[190:191] op_sel:[0,0,0] op_sel_hi:[1,0,1]
	ds_read_b128 v[220:223], v2 offset:58608
	s_waitcnt lgkmcnt(12)
	v_pk_fma_f32 v[192:193], v[224:225], v[176:177], v[192:193] op_sel:[0,0,0] op_sel_hi:[1,0,1]
	v_pk_fma_f32 v[194:195], v[226:227], v[176:177], v[194:195] op_sel:[0,0,0] op_sel_hi:[1,0,1]
	ds_read_b128 v[224:227], v2 offset:58624
	s_waitcnt lgkmcnt(12)
	v_pk_fma_f32 v[196:197], v[228:229], v[176:177], v[196:197] op_sel:[0,0,0] op_sel_hi:[1,0,1]
	v_pk_fma_f32 v[198:199], v[230:231], v[176:177], v[198:199] op_sel:[0,0,0] op_sel_hi:[1,0,1]
	ds_read_b128 v[228:231], v2 offset:58640
	s_waitcnt lgkmcnt(12)
	v_pk_fma_f32 v[200:201], v[240:241], v[176:177], v[200:201] op_sel:[0,0,0] op_sel_hi:[1,0,1]
	v_pk_fma_f32 v[202:203], v[242:243], v[176:177], v[202:203] op_sel:[0,0,0] op_sel_hi:[1,0,1]
	ds_read_b128 v[240:243], v2 offset:58656
	s_waitcnt lgkmcnt(12)
	v_pk_fma_f32 v[204:205], v[244:245], v[176:177], v[204:205] op_sel:[0,0,0] op_sel_hi:[1,0,1]
	v_pk_fma_f32 v[206:207], v[246:247], v[176:177], v[206:207] op_sel:[0,0,0] op_sel_hi:[1,0,1]
	ds_read_b128 v[244:247], v2 offset:58672
	s_waitcnt lgkmcnt(12)
	v_pk_fma_f32 v[178:179], v[40:41], v[176:177], v[178:179] op_sel:[0,1,0] op_sel_hi:[1,1,1]
	v_cvt_pk_bf16_f32 v232, v177, v2
	ds_write_b16 v113, v232 offset:32400
	ds_read_b128 v[38:41], v2 offset:58688
	s_waitcnt lgkmcnt(13)
	v_pk_fma_f32 v[180:181], v[42:43], v[176:177], v[180:181] op_sel:[0,1,0] op_sel_hi:[1,1,1]
	v_pk_fma_f32 v[182:183], v[44:45], v[176:177], v[182:183] op_sel:[0,1,0] op_sel_hi:[1,1,1]
	ds_read_b128 v[42:45], v2 offset:58704
	s_waitcnt lgkmcnt(13)
	v_pk_fma_f32 v[184:185], v[46:47], v[176:177], v[184:185] op_sel:[0,1,0] op_sel_hi:[1,1,1]
	v_pk_fma_f32 v[186:187], v[48:49], v[176:177], v[186:187] op_sel:[0,1,0] op_sel_hi:[1,1,1]
	ds_read_b128 v[46:49], v2 offset:58720
	s_waitcnt lgkmcnt(13)
	v_pk_fma_f32 v[188:189], v[50:51], v[176:177], v[188:189] op_sel:[0,1,0] op_sel_hi:[1,1,1]
	v_pk_fma_f32 v[190:191], v[52:53], v[176:177], v[190:191] op_sel:[0,1,0] op_sel_hi:[1,1,1]
	ds_read_b128 v[50:53], v2 offset:58736
	s_waitcnt lgkmcnt(12)
	v_pk_fma_f32 v[192:193], v[208:209], v[176:177], v[192:193] op_sel:[0,1,0] op_sel_hi:[1,1,1]
	v_pk_fma_f32 v[194:195], v[210:211], v[176:177], v[194:195] op_sel:[0,1,0] op_sel_hi:[1,1,1]
	ds_read_b128 v[208:211], v2 offset:58768
	s_waitcnt lgkmcnt(12)
	v_pk_fma_f32 v[196:197], v[212:213], v[176:177], v[196:197] op_sel:[0,1,0] op_sel_hi:[1,1,1]
	v_pk_fma_f32 v[198:199], v[214:215], v[176:177], v[198:199] op_sel:[0,1,0] op_sel_hi:[1,1,1]
	ds_read_b128 v[212:215], v2 offset:58784
	s_waitcnt lgkmcnt(12)
	v_pk_fma_f32 v[200:201], v[216:217], v[176:177], v[200:201] op_sel:[0,1,0] op_sel_hi:[1,1,1]
	v_pk_fma_f32 v[202:203], v[218:219], v[176:177], v[202:203] op_sel:[0,1,0] op_sel_hi:[1,1,1]
	ds_read_b128 v[216:219], v2 offset:58800
	s_waitcnt lgkmcnt(12)
	v_pk_fma_f32 v[204:205], v[220:221], v[176:177], v[204:205] op_sel:[0,1,0] op_sel_hi:[1,1,1]
	v_pk_fma_f32 v[206:207], v[222:223], v[176:177], v[206:207] op_sel:[0,1,0] op_sel_hi:[1,1,1]
	ds_read_b128 v[220:223], v2 offset:58816
	s_waitcnt lgkmcnt(12)
	v_pk_fma_f32 v[178:179], v[226:227], v[178:179], v[178:179] op_sel:[0,0,0] op_sel_hi:[1,0,1]
	v_cvt_pk_bf16_f32 v233, v178, v2
	ds_write_b16 v113, v233 offset:32544
	ds_read_b128 v[224:227], v2 offset:58832
	s_waitcnt lgkmcnt(13)
	v_pk_fma_f32 v[180:181], v[228:229], v[178:179], v[180:181] op_sel:[0,0,0] op_sel_hi:[1,0,1]
	v_pk_fma_f32 v[182:183], v[230:231], v[178:179], v[182:183] op_sel:[0,0,0] op_sel_hi:[1,0,1]
	ds_read_b128 v[228:231], v2 offset:58848
	s_waitcnt lgkmcnt(13)
	v_pk_fma_f32 v[184:185], v[240:241], v[178:179], v[184:185] op_sel:[0,0,0] op_sel_hi:[1,0,1]
	v_pk_fma_f32 v[186:187], v[242:243], v[178:179], v[186:187] op_sel:[0,0,0] op_sel_hi:[1,0,1]
	ds_read_b128 v[240:243], v2 offset:58864
	s_waitcnt lgkmcnt(13)
	v_pk_fma_f32 v[188:189], v[244:245], v[178:179], v[188:189] op_sel:[0,0,0] op_sel_hi:[1,0,1]
	v_pk_fma_f32 v[190:191], v[246:247], v[178:179], v[190:191] op_sel:[0,0,0] op_sel_hi:[1,0,1]
	ds_read_b128 v[244:247], v2 offset:58896
	s_waitcnt lgkmcnt(12)
	v_pk_fma_f32 v[192:193], v[38:39], v[178:179], v[192:193] op_sel:[0,0,0] op_sel_hi:[1,0,1]
	v_pk_fma_f32 v[194:195], v[40:41], v[178:179], v[194:195] op_sel:[0,0,0] op_sel_hi:[1,0,1]
	ds_read_b128 v[38:41], v2 offset:58912
	s_waitcnt lgkmcnt(12)
	v_pk_fma_f32 v[196:197], v[42:43], v[178:179], v[196:197] op_sel:[0,0,0] op_sel_hi:[1,0,1]
	v_pk_fma_f32 v[198:199], v[44:45], v[178:179], v[198:199] op_sel:[0,0,0] op_sel_hi:[1,0,1]
	ds_read_b128 v[42:45], v2 offset:58928
	s_waitcnt lgkmcnt(12)
	v_pk_fma_f32 v[200:201], v[46:47], v[178:179], v[200:201] op_sel:[0,0,0] op_sel_hi:[1,0,1]
	v_pk_fma_f32 v[202:203], v[48:49], v[178:179], v[202:203] op_sel:[0,0,0] op_sel_hi:[1,0,1]
	ds_read_b128 v[46:49], v2 offset:58944
	s_waitcnt lgkmcnt(12)
	v_pk_fma_f32 v[204:205], v[50:51], v[178:179], v[204:205] op_sel:[0,0,0] op_sel_hi:[1,0,1]
	v_pk_fma_f32 v[206:207], v[52:53], v[178:179], v[206:207] op_sel:[0,0,0] op_sel_hi:[1,0,1]
	ds_read_b128 v[50:53], v2 offset:58960
	s_waitcnt lgkmcnt(12)
	v_pk_fma_f32 v[180:181], v[208:209], v[178:179], v[180:181] op_sel:[0,1,0] op_sel_hi:[1,1,1]
	v_pk_fma_f32 v[182:183], v[210:211], v[178:179], v[182:183] op_sel:[0,1,0] op_sel_hi:[1,1,1]
	v_cvt_pk_bf16_f32 v248, v179, v2
	ds_write_b16 v113, v248 offset:32688
	ds_read_b128 v[208:211], v2 offset:58976
	s_waitcnt lgkmcnt(13)
	v_pk_fma_f32 v[184:185], v[212:213], v[178:179], v[184:185] op_sel:[0,1,0] op_sel_hi:[1,1,1]
	v_pk_fma_f32 v[186:187], v[214:215], v[178:179], v[186:187] op_sel:[0,1,0] op_sel_hi:[1,1,1]
	ds_read_b128 v[212:215], v2 offset:58992
	s_waitcnt lgkmcnt(13)
	v_pk_fma_f32 v[188:189], v[216:217], v[178:179], v[188:189] op_sel:[0,1,0] op_sel_hi:[1,1,1]
	v_pk_fma_f32 v[190:191], v[218:219], v[178:179], v[190:191] op_sel:[0,1,0] op_sel_hi:[1,1,1]
	ds_read_b128 v[216:219], v2 offset:59024
	s_waitcnt lgkmcnt(13)
	v_pk_fma_f32 v[192:193], v[220:221], v[178:179], v[192:193] op_sel:[0,1,0] op_sel_hi:[1,1,1]
	v_pk_fma_f32 v[194:195], v[222:223], v[178:179], v[194:195] op_sel:[0,1,0] op_sel_hi:[1,1,1]
	ds_read_b128 v[220:223], v2 offset:59040
	s_waitcnt lgkmcnt(12)
	v_pk_fma_f32 v[196:197], v[224:225], v[178:179], v[196:197] op_sel:[0,1,0] op_sel_hi:[1,1,1]
	v_pk_fma_f32 v[198:199], v[226:227], v[178:179], v[198:199] op_sel:[0,1,0] op_sel_hi:[1,1,1]
	ds_read_b128 v[224:227], v2 offset:59056
	s_waitcnt lgkmcnt(12)
	v_pk_fma_f32 v[200:201], v[228:229], v[178:179], v[200:201] op_sel:[0,1,0] op_sel_hi:[1,1,1]
	v_pk_fma_f32 v[202:203], v[230:231], v[178:179], v[202:203] op_sel:[0,1,0] op_sel_hi:[1,1,1]
	ds_read_b128 v[228:231], v2 offset:59072
	s_waitcnt lgkmcnt(12)
	v_pk_fma_f32 v[204:205], v[240:241], v[178:179], v[204:205] op_sel:[0,1,0] op_sel_hi:[1,1,1]
	v_pk_fma_f32 v[206:207], v[242:243], v[178:179], v[206:207] op_sel:[0,1,0] op_sel_hi:[1,1,1]
	ds_read_b128 v[240:243], v2 offset:59088
	s_waitcnt lgkmcnt(12)
	v_pk_fma_f32 v[180:181], v[244:245], v[180:181], v[180:181] op_sel:[0,0,0] op_sel_hi:[1,0,1]
	v_pk_fma_f32 v[182:183], v[246:247], v[180:181], v[182:183] op_sel:[0,0,0] op_sel_hi:[1,0,1]
	v_cvt_pk_bf16_f32 v3, v180, v2
	ds_write_b16 v113, v3 offset:32832
	ds_read_b128 v[244:247], v2 offset:59104
	s_waitcnt lgkmcnt(13)
	v_pk_fma_f32 v[184:185], v[38:39], v[180:181], v[184:185] op_sel:[0,0,0] op_sel_hi:[1,0,1]
	v_pk_fma_f32 v[186:187], v[40:41], v[180:181], v[186:187] op_sel:[0,0,0] op_sel_hi:[1,0,1]
	ds_read_b128 v[38:41], v2 offset:59120
	s_waitcnt lgkmcnt(13)
	v_pk_fma_f32 v[188:189], v[42:43], v[180:181], v[188:189] op_sel:[0,0,0] op_sel_hi:[1,0,1]
	v_pk_fma_f32 v[190:191], v[44:45], v[180:181], v[190:191] op_sel:[0,0,0] op_sel_hi:[1,0,1]
	ds_read_b128 v[42:45], v2 offset:59152
	s_waitcnt lgkmcnt(13)
	v_pk_fma_f32 v[192:193], v[46:47], v[180:181], v[192:193] op_sel:[0,0,0] op_sel_hi:[1,0,1]
	v_pk_fma_f32 v[194:195], v[48:49], v[180:181], v[194:195] op_sel:[0,0,0] op_sel_hi:[1,0,1]
	ds_read_b128 v[46:49], v2 offset:59168
	s_waitcnt lgkmcnt(13)
	v_pk_fma_f32 v[196:197], v[50:51], v[180:181], v[196:197] op_sel:[0,0,0] op_sel_hi:[1,0,1]
	v_pk_fma_f32 v[198:199], v[52:53], v[180:181], v[198:199] op_sel:[0,0,0] op_sel_hi:[1,0,1]
	ds_read_b128 v[50:53], v2 offset:59184
	s_waitcnt lgkmcnt(12)
	v_pk_fma_f32 v[200:201], v[208:209], v[180:181], v[200:201] op_sel:[0,0,0] op_sel_hi:[1,0,1]
	v_pk_fma_f32 v[202:203], v[210:211], v[180:181], v[202:203] op_sel:[0,0,0] op_sel_hi:[1,0,1]
	ds_read_b128 v[208:211], v2 offset:59200
	s_waitcnt lgkmcnt(12)
	v_pk_fma_f32 v[204:205], v[212:213], v[180:181], v[204:205] op_sel:[0,0,0] op_sel_hi:[1,0,1]
	v_pk_fma_f32 v[206:207], v[214:215], v[180:181], v[206:207] op_sel:[0,0,0] op_sel_hi:[1,0,1]
	ds_read_b128 v[212:215], v2 offset:59216
	s_waitcnt lgkmcnt(12)
	v_pk_fma_f32 v[182:183], v[218:219], v[180:181], v[182:183] op_sel:[0,1,0] op_sel_hi:[1,1,1]
	v_cvt_pk_bf16_f32 v232, v181, v2
	ds_write_b16 v113, v232 offset:32976
	ds_read_b128 v[216:219], v2 offset:59232
	s_waitcnt lgkmcnt(13)
	v_pk_fma_f32 v[184:185], v[220:221], v[180:181], v[184:185] op_sel:[0,1,0] op_sel_hi:[1,1,1]
	v_pk_fma_f32 v[186:187], v[222:223], v[180:181], v[186:187] op_sel:[0,1,0] op_sel_hi:[1,1,1]
	ds_read_b128 v[220:223], v2 offset:59248
	s_waitcnt lgkmcnt(13)
	v_pk_fma_f32 v[188:189], v[224:225], v[180:181], v[188:189] op_sel:[0,1,0] op_sel_hi:[1,1,1]
	v_pk_fma_f32 v[190:191], v[226:227], v[180:181], v[190:191] op_sel:[0,1,0] op_sel_hi:[1,1,1]
	ds_read_b128 v[224:227], v2 offset:59296
	s_waitcnt lgkmcnt(13)
	v_pk_fma_f32 v[192:193], v[228:229], v[180:181], v[192:193] op_sel:[0,1,0] op_sel_hi:[1,1,1]
	v_pk_fma_f32 v[194:195], v[230:231], v[180:181], v[194:195] op_sel:[0,1,0] op_sel_hi:[1,1,1]
	ds_read_b128 v[228:231], v2 offset:59312
	s_waitcnt lgkmcnt(13)
	v_pk_fma_f32 v[196:197], v[240:241], v[180:181], v[196:197] op_sel:[0,1,0] op_sel_hi:[1,1,1]
	v_pk_fma_f32 v[198:199], v[242:243], v[180:181], v[198:199] op_sel:[0,1,0] op_sel_hi:[1,1,1]
	ds_read_b128 v[240:243], v2 offset:59328
	s_waitcnt lgkmcnt(12)
	v_pk_fma_f32 v[200:201], v[244:245], v[180:181], v[200:201] op_sel:[0,1,0] op_sel_hi:[1,1,1]
	v_pk_fma_f32 v[202:203], v[246:247], v[180:181], v[202:203] op_sel:[0,1,0] op_sel_hi:[1,1,1]
	ds_read_b128 v[244:247], v2 offset:59344
	s_waitcnt lgkmcnt(12)
	v_pk_fma_f32 v[204:205], v[38:39], v[180:181], v[204:205] op_sel:[0,1,0] op_sel_hi:[1,1,1]
	v_pk_fma_f32 v[206:207], v[40:41], v[180:181], v[206:207] op_sel:[0,1,0] op_sel_hi:[1,1,1]
	ds_read_b128 v[38:41], v2 offset:59360
	s_waitcnt lgkmcnt(12)
	v_pk_fma_f32 v[182:183], v[44:45], v[182:183], v[182:183] op_sel:[0,0,0] op_sel_hi:[1,0,1]
	v_cvt_pk_bf16_f32 v233, v182, v2
	ds_write_b16 v113, v233 offset:33120
	ds_read_b128 v[42:45], v2 offset:59376
	s_waitcnt lgkmcnt(13)
	v_pk_fma_f32 v[184:185], v[46:47], v[182:183], v[184:185] op_sel:[0,0,0] op_sel_hi:[1,0,1]
	v_pk_fma_f32 v[186:187], v[48:49], v[182:183], v[186:187] op_sel:[0,0,0] op_sel_hi:[1,0,1]
	ds_read_b128 v[46:49], v2 offset:59424
	s_waitcnt lgkmcnt(13)
	v_pk_fma_f32 v[188:189], v[50:51], v[182:183], v[188:189] op_sel:[0,0,0] op_sel_hi:[1,0,1]
	v_pk_fma_f32 v[190:191], v[52:53], v[182:183], v[190:191] op_sel:[0,0,0] op_sel_hi:[1,0,1]
	ds_read_b128 v[50:53], v2 offset:59440
	s_waitcnt lgkmcnt(13)
	v_pk_fma_f32 v[192:193], v[208:209], v[182:183], v[192:193] op_sel:[0,0,0] op_sel_hi:[1,0,1]
	v_pk_fma_f32 v[194:195], v[210:211], v[182:183], v[194:195] op_sel:[0,0,0] op_sel_hi:[1,0,1]
	ds_read_b128 v[208:211], v2 offset:59456
	s_waitcnt lgkmcnt(13)
	v_pk_fma_f32 v[196:197], v[212:213], v[182:183], v[196:197] op_sel:[0,0,0] op_sel_hi:[1,0,1]
	v_pk_fma_f32 v[198:199], v[214:215], v[182:183], v[198:199] op_sel:[0,0,0] op_sel_hi:[1,0,1]
	ds_read_b128 v[212:215], v2 offset:59472
	s_waitcnt lgkmcnt(12)
	v_pk_fma_f32 v[200:201], v[216:217], v[182:183], v[200:201] op_sel:[0,0,0] op_sel_hi:[1,0,1]
	v_pk_fma_f32 v[202:203], v[218:219], v[182:183], v[202:203] op_sel:[0,0,0] op_sel_hi:[1,0,1]
	ds_read_b128 v[216:219], v2 offset:59488
	s_waitcnt lgkmcnt(12)
	v_pk_fma_f32 v[204:205], v[220:221], v[182:183], v[204:205] op_sel:[0,0,0] op_sel_hi:[1,0,1]
	v_pk_fma_f32 v[206:207], v[222:223], v[182:183], v[206:207] op_sel:[0,0,0] op_sel_hi:[1,0,1]
	ds_read_b128 v[220:223], v2 offset:59504
	s_waitcnt lgkmcnt(12)
	v_pk_fma_f32 v[184:185], v[224:225], v[182:183], v[184:185] op_sel:[0,1,0] op_sel_hi:[1,1,1]
	v_pk_fma_f32 v[186:187], v[226:227], v[182:183], v[186:187] op_sel:[0,1,0] op_sel_hi:[1,1,1]
	v_cvt_pk_bf16_f32 v248, v183, v2
	ds_write_b16 v113, v248 offset:33264
	ds_read_b128 v[224:227], v2 offset:59552
	s_waitcnt lgkmcnt(13)
	v_pk_fma_f32 v[188:189], v[228:229], v[182:183], v[188:189] op_sel:[0,1,0] op_sel_hi:[1,1,1]
	v_pk_fma_f32 v[190:191], v[230:231], v[182:183], v[190:191] op_sel:[0,1,0] op_sel_hi:[1,1,1]
	ds_read_b128 v[228:231], v2 offset:59568
	s_waitcnt lgkmcnt(13)
	v_pk_fma_f32 v[192:193], v[240:241], v[182:183], v[192:193] op_sel:[0,1,0] op_sel_hi:[1,1,1]
	v_pk_fma_f32 v[194:195], v[242:243], v[182:183], v[194:195] op_sel:[0,1,0] op_sel_hi:[1,1,1]
	ds_read_b128 v[240:243], v2 offset:59584
	s_waitcnt lgkmcnt(13)
	v_pk_fma_f32 v[196:197], v[244:245], v[182:183], v[196:197] op_sel:[0,1,0] op_sel_hi:[1,1,1]
	v_pk_fma_f32 v[198:199], v[246:247], v[182:183], v[198:199] op_sel:[0,1,0] op_sel_hi:[1,1,1]
	ds_read_b128 v[244:247], v2 offset:59600
	s_waitcnt lgkmcnt(13)
	v_pk_fma_f32 v[200:201], v[38:39], v[182:183], v[200:201] op_sel:[0,1,0] op_sel_hi:[1,1,1]
	v_pk_fma_f32 v[202:203], v[40:41], v[182:183], v[202:203] op_sel:[0,1,0] op_sel_hi:[1,1,1]
	ds_read_b128 v[38:41], v2 offset:59616
	s_waitcnt lgkmcnt(12)
	v_pk_fma_f32 v[204:205], v[42:43], v[182:183], v[204:205] op_sel:[0,1,0] op_sel_hi:[1,1,1]
	v_pk_fma_f32 v[206:207], v[44:45], v[182:183], v[206:207] op_sel:[0,1,0] op_sel_hi:[1,1,1]
	ds_read_b128 v[42:45], v2 offset:59632
	s_waitcnt lgkmcnt(12)
	v_pk_fma_f32 v[184:185], v[46:47], v[184:185], v[184:185] op_sel:[0,0,0] op_sel_hi:[1,0,1]
	v_pk_fma_f32 v[186:187], v[48:49], v[184:185], v[186:187] op_sel:[0,0,0] op_sel_hi:[1,0,1]
	v_cvt_pk_bf16_f32 v3, v184, v2
	ds_write_b16 v113, v3 offset:33408
	ds_read_b128 v[46:49], v2 offset:59680
	s_waitcnt lgkmcnt(13)
	v_pk_fma_f32 v[188:189], v[50:51], v[184:185], v[188:189] op_sel:[0,0,0] op_sel_hi:[1,0,1]
	v_pk_fma_f32 v[190:191], v[52:53], v[184:185], v[190:191] op_sel:[0,0,0] op_sel_hi:[1,0,1]
	ds_read_b128 v[50:53], v2 offset:59696
	s_waitcnt lgkmcnt(13)
	v_pk_fma_f32 v[192:193], v[208:209], v[184:185], v[192:193] op_sel:[0,0,0] op_sel_hi:[1,0,1]
	v_pk_fma_f32 v[194:195], v[210:211], v[184:185], v[194:195] op_sel:[0,0,0] op_sel_hi:[1,0,1]
	ds_read_b128 v[208:211], v2 offset:59712
	s_waitcnt lgkmcnt(13)
	v_pk_fma_f32 v[196:197], v[212:213], v[184:185], v[196:197] op_sel:[0,0,0] op_sel_hi:[1,0,1]
	v_pk_fma_f32 v[198:199], v[214:215], v[184:185], v[198:199] op_sel:[0,0,0] op_sel_hi:[1,0,1]
	ds_read_b128 v[212:215], v2 offset:59728
	s_waitcnt lgkmcnt(13)
	v_pk_fma_f32 v[200:201], v[216:217], v[184:185], v[200:201] op_sel:[0,0,0] op_sel_hi:[1,0,1]
	v_pk_fma_f32 v[202:203], v[218:219], v[184:185], v[202:203] op_sel:[0,0,0] op_sel_hi:[1,0,1]
	ds_read_b128 v[216:219], v2 offset:59744
	s_waitcnt lgkmcnt(13)
	v_pk_fma_f32 v[204:205], v[220:221], v[184:185], v[204:205] op_sel:[0,0,0] op_sel_hi:[1,0,1]
	v_pk_fma_f32 v[206:207], v[222:223], v[184:185], v[206:207] op_sel:[0,0,0] op_sel_hi:[1,0,1]
	ds_read_b128 v[220:223], v2 offset:59760
	s_waitcnt lgkmcnt(12)
	v_pk_fma_f32 v[186:187], v[226:227], v[184:185], v[186:187] op_sel:[0,1,0] op_sel_hi:[1,1,1]
	v_cvt_pk_bf16_f32 v232, v185, v2
	ds_write_b16 v113, v232 offset:33552
	ds_read_b128 v[224:227], v2 offset:59824
	s_waitcnt lgkmcnt(13)
	v_pk_fma_f32 v[188:189], v[228:229], v[184:185], v[188:189] op_sel:[0,1,0] op_sel_hi:[1,1,1]
	v_pk_fma_f32 v[190:191], v[230:231], v[184:185], v[190:191] op_sel:[0,1,0] op_sel_hi:[1,1,1]
	ds_read_b128 v[228:231], v2 offset:59840
	s_waitcnt lgkmcnt(13)
	v_pk_fma_f32 v[192:193], v[240:241], v[184:185], v[192:193] op_sel:[0,1,0] op_sel_hi:[1,1,1]
	v_pk_fma_f32 v[194:195], v[242:243], v[184:185], v[194:195] op_sel:[0,1,0] op_sel_hi:[1,1,1]
	ds_read_b128 v[240:243], v2 offset:59856
	s_waitcnt lgkmcnt(13)
	v_pk_fma_f32 v[196:197], v[244:245], v[184:185], v[196:197] op_sel:[0,1,0] op_sel_hi:[1,1,1]
	v_pk_fma_f32 v[198:199], v[246:247], v[184:185], v[198:199] op_sel:[0,1,0] op_sel_hi:[1,1,1]
	ds_read_b128 v[244:247], v2 offset:59872
	s_waitcnt lgkmcnt(13)
	v_pk_fma_f32 v[200:201], v[38:39], v[184:185], v[200:201] op_sel:[0,1,0] op_sel_hi:[1,1,1]
	v_pk_fma_f32 v[202:203], v[40:41], v[184:185], v[202:203] op_sel:[0,1,0] op_sel_hi:[1,1,1]
	ds_read_b128 v[38:41], v2 offset:59888
	s_waitcnt lgkmcnt(13)
	v_pk_fma_f32 v[204:205], v[42:43], v[184:185], v[204:205] op_sel:[0,1,0] op_sel_hi:[1,1,1]
	v_pk_fma_f32 v[206:207], v[44:45], v[184:185], v[206:207] op_sel:[0,1,0] op_sel_hi:[1,1,1]
	ds_read_b128 v[42:45], v2 offset:59952
	s_waitcnt lgkmcnt(12)
	v_pk_fma_f32 v[186:187], v[48:49], v[186:187], v[186:187] op_sel:[0,0,0] op_sel_hi:[1,0,1]
	v_cvt_pk_bf16_f32 v233, v186, v2
	ds_write_b16 v113, v233 offset:33696
	ds_read_b128 v[46:49], v2 offset:59968
	s_waitcnt lgkmcnt(13)
	v_pk_fma_f32 v[188:189], v[50:51], v[186:187], v[188:189] op_sel:[0,0,0] op_sel_hi:[1,0,1]
	v_pk_fma_f32 v[190:191], v[52:53], v[186:187], v[190:191] op_sel:[0,0,0] op_sel_hi:[1,0,1]
	ds_read_b128 v[50:53], v2 offset:59984
	s_waitcnt lgkmcnt(13)
	v_pk_fma_f32 v[192:193], v[208:209], v[186:187], v[192:193] op_sel:[0,0,0] op_sel_hi:[1,0,1]
	v_pk_fma_f32 v[194:195], v[210:211], v[186:187], v[194:195] op_sel:[0,0,0] op_sel_hi:[1,0,1]
	ds_read_b128 v[208:211], v2 offset:60000
	s_waitcnt lgkmcnt(13)
	v_pk_fma_f32 v[196:197], v[212:213], v[186:187], v[196:197] op_sel:[0,0,0] op_sel_hi:[1,0,1]
	v_pk_fma_f32 v[198:199], v[214:215], v[186:187], v[198:199] op_sel:[0,0,0] op_sel_hi:[1,0,1]
	ds_read_b128 v[212:215], v2 offset:60016
	s_waitcnt lgkmcnt(13)
	v_pk_fma_f32 v[200:201], v[216:217], v[186:187], v[200:201] op_sel:[0,0,0] op_sel_hi:[1,0,1]
	v_pk_fma_f32 v[202:203], v[218:219], v[186:187], v[202:203] op_sel:[0,0,0] op_sel_hi:[1,0,1]
	ds_read_b128 v[216:219], v2 offset:60080
	s_waitcnt lgkmcnt(13)
	v_pk_fma_f32 v[204:205], v[220:221], v[186:187], v[204:205] op_sel:[0,0,0] op_sel_hi:[1,0,1]
	v_pk_fma_f32 v[206:207], v[222:223], v[186:187], v[206:207] op_sel:[0,0,0] op_sel_hi:[1,0,1]
	ds_read_b128 v[220:223], v2 offset:60096
	s_waitcnt lgkmcnt(12)
	v_pk_fma_f32 v[188:189], v[224:225], v[186:187], v[188:189] op_sel:[0,1,0] op_sel_hi:[1,1,1]
	v_pk_fma_f32 v[190:191], v[226:227], v[186:187], v[190:191] op_sel:[0,1,0] op_sel_hi:[1,1,1]
	v_cvt_pk_bf16_f32 v248, v187, v2
	ds_write_b16 v113, v248 offset:33840
	ds_read_b128 v[224:227], v2 offset:60112
	s_waitcnt lgkmcnt(13)
	v_pk_fma_f32 v[192:193], v[228:229], v[186:187], v[192:193] op_sel:[0,1,0] op_sel_hi:[1,1,1]
	v_pk_fma_f32 v[194:195], v[230:231], v[186:187], v[194:195] op_sel:[0,1,0] op_sel_hi:[1,1,1]
	ds_read_b128 v[228:231], v2 offset:60128
	s_waitcnt lgkmcnt(13)
	v_pk_fma_f32 v[196:197], v[240:241], v[186:187], v[196:197] op_sel:[0,1,0] op_sel_hi:[1,1,1]
	v_pk_fma_f32 v[198:199], v[242:243], v[186:187], v[198:199] op_sel:[0,1,0] op_sel_hi:[1,1,1]
	ds_read_b128 v[240:243], v2 offset:60144
	s_waitcnt lgkmcnt(13)
	v_pk_fma_f32 v[200:201], v[244:245], v[186:187], v[200:201] op_sel:[0,1,0] op_sel_hi:[1,1,1]
	v_pk_fma_f32 v[202:203], v[246:247], v[186:187], v[202:203] op_sel:[0,1,0] op_sel_hi:[1,1,1]
	ds_read_b128 v[244:247], v2 offset:60208
	s_waitcnt lgkmcnt(13)
	v_pk_fma_f32 v[204:205], v[38:39], v[186:187], v[204:205] op_sel:[0,1,0] op_sel_hi:[1,1,1]
	v_pk_fma_f32 v[206:207], v[40:41], v[186:187], v[206:207] op_sel:[0,1,0] op_sel_hi:[1,1,1]
	ds_read_b128 v[38:41], v2 offset:60224
	s_waitcnt lgkmcnt(13)
	v_pk_fma_f32 v[188:189], v[42:43], v[188:189], v[188:189] op_sel:[0,0,0] op_sel_hi:[1,0,1]
	v_pk_fma_f32 v[190:191], v[44:45], v[188:189], v[190:191] op_sel:[0,0,0] op_sel_hi:[1,0,1]
	v_cvt_pk_bf16_f32 v3, v188, v2
	ds_write_b16 v113, v3 offset:33984
	ds_read_b128 v[42:45], v2 offset:60240
	s_waitcnt lgkmcnt(13)
	v_pk_fma_f32 v[192:193], v[46:47], v[188:189], v[192:193] op_sel:[0,0,0] op_sel_hi:[1,0,1]
	v_pk_fma_f32 v[194:195], v[48:49], v[188:189], v[194:195] op_sel:[0,0,0] op_sel_hi:[1,0,1]
	ds_read_b128 v[46:49], v2 offset:60256
	s_waitcnt lgkmcnt(13)
	v_pk_fma_f32 v[196:197], v[50:51], v[188:189], v[196:197] op_sel:[0,0,0] op_sel_hi:[1,0,1]
	v_pk_fma_f32 v[198:199], v[52:53], v[188:189], v[198:199] op_sel:[0,0,0] op_sel_hi:[1,0,1]
	ds_read_b128 v[50:53], v2 offset:60272
	s_waitcnt lgkmcnt(13)
	v_pk_fma_f32 v[200:201], v[208:209], v[188:189], v[200:201] op_sel:[0,0,0] op_sel_hi:[1,0,1]
	v_pk_fma_f32 v[202:203], v[210:211], v[188:189], v[202:203] op_sel:[0,0,0] op_sel_hi:[1,0,1]
	ds_read_b128 v[208:211], v2 offset:60352
	s_waitcnt lgkmcnt(13)
	v_pk_fma_f32 v[204:205], v[212:213], v[188:189], v[204:205] op_sel:[0,0,0] op_sel_hi:[1,0,1]
	v_pk_fma_f32 v[206:207], v[214:215], v[188:189], v[206:207] op_sel:[0,0,0] op_sel_hi:[1,0,1]
	ds_read_b128 v[212:215], v2 offset:60368
	s_waitcnt lgkmcnt(13)
	v_pk_fma_f32 v[190:191], v[218:219], v[188:189], v[190:191] op_sel:[0,1,0] op_sel_hi:[1,1,1]
	v_cvt_pk_bf16_f32 v232, v189, v2
	ds_write_b16 v113, v232 offset:34128
	ds_read_b128 v[216:219], v2 offset:60384
	s_waitcnt lgkmcnt(14)
	v_pk_fma_f32 v[192:193], v[220:221], v[188:189], v[192:193] op_sel:[0,1,0] op_sel_hi:[1,1,1]
	v_pk_fma_f32 v[194:195], v[222:223], v[188:189], v[194:195] op_sel:[0,1,0] op_sel_hi:[1,1,1]
	ds_read_b128 v[220:223], v2 offset:60400
	s_waitcnt lgkmcnt(13)
	v_pk_fma_f32 v[196:197], v[224:225], v[188:189], v[196:197] op_sel:[0,1,0] op_sel_hi:[1,1,1]
	v_pk_fma_f32 v[198:199], v[226:227], v[188:189], v[198:199] op_sel:[0,1,0] op_sel_hi:[1,1,1]
	ds_read_b128 v[224:227], v2 offset:60480
	s_waitcnt lgkmcnt(13)
	v_pk_fma_f32 v[200:201], v[228:229], v[188:189], v[200:201] op_sel:[0,1,0] op_sel_hi:[1,1,1]
	v_pk_fma_f32 v[202:203], v[230:231], v[188:189], v[202:203] op_sel:[0,1,0] op_sel_hi:[1,1,1]
	ds_read_b128 v[228:231], v2 offset:60496
	s_waitcnt lgkmcnt(13)
	v_pk_fma_f32 v[204:205], v[240:241], v[188:189], v[204:205] op_sel:[0,1,0] op_sel_hi:[1,1,1]
	v_pk_fma_f32 v[206:207], v[242:243], v[188:189], v[206:207] op_sel:[0,1,0] op_sel_hi:[1,1,1]
	ds_read_b128 v[240:243], v2 offset:60512
	s_waitcnt lgkmcnt(13)
	v_pk_fma_f32 v[190:191], v[246:247], v[190:191], v[190:191] op_sel:[0,0,0] op_sel_hi:[1,0,1]
	v_cvt_pk_bf16_f32 v233, v190, v2
	ds_write_b16 v113, v233 offset:34272
	ds_read_b128 v[244:247], v2 offset:60528
	s_waitcnt lgkmcnt(14)
	v_pk_fma_f32 v[192:193], v[38:39], v[190:191], v[192:193] op_sel:[0,0,0] op_sel_hi:[1,0,1]
	v_pk_fma_f32 v[194:195], v[40:41], v[190:191], v[194:195] op_sel:[0,0,0] op_sel_hi:[1,0,1]
	ds_read_b128 v[38:41], v2 offset:60608
	s_waitcnt lgkmcnt(13)
	v_pk_fma_f32 v[196:197], v[42:43], v[190:191], v[196:197] op_sel:[0,0,0] op_sel_hi:[1,0,1]
	v_pk_fma_f32 v[198:199], v[44:45], v[190:191], v[198:199] op_sel:[0,0,0] op_sel_hi:[1,0,1]
	ds_read_b128 v[42:45], v2 offset:60624
	s_waitcnt lgkmcnt(13)
	v_pk_fma_f32 v[200:201], v[46:47], v[190:191], v[200:201] op_sel:[0,0,0] op_sel_hi:[1,0,1]
	v_pk_fma_f32 v[202:203], v[48:49], v[190:191], v[202:203] op_sel:[0,0,0] op_sel_hi:[1,0,1]
	ds_read_b128 v[46:49], v2 offset:60640
	s_waitcnt lgkmcnt(13)
	v_pk_fma_f32 v[204:205], v[50:51], v[190:191], v[204:205] op_sel:[0,0,0] op_sel_hi:[1,0,1]
	v_pk_fma_f32 v[206:207], v[52:53], v[190:191], v[206:207] op_sel:[0,0,0] op_sel_hi:[1,0,1]
	ds_read_b128 v[50:53], v2 offset:60656
	s_waitcnt lgkmcnt(13)
	v_pk_fma_f32 v[192:193], v[208:209], v[190:191], v[192:193] op_sel:[0,1,0] op_sel_hi:[1,1,1]
	v_pk_fma_f32 v[194:195], v[210:211], v[190:191], v[194:195] op_sel:[0,1,0] op_sel_hi:[1,1,1]
	v_cvt_pk_bf16_f32 v248, v191, v2
	ds_write_b16 v113, v248 offset:34416
	ds_read_b128 v[208:211], v2 offset:60736
	s_waitcnt lgkmcnt(14)
	v_pk_fma_f32 v[196:197], v[212:213], v[190:191], v[196:197] op_sel:[0,1,0] op_sel_hi:[1,1,1]
	v_pk_fma_f32 v[198:199], v[214:215], v[190:191], v[198:199] op_sel:[0,1,0] op_sel_hi:[1,1,1]
	ds_read_b128 v[212:215], v2 offset:60752
	s_waitcnt lgkmcnt(13)
	v_pk_fma_f32 v[200:201], v[216:217], v[190:191], v[200:201] op_sel:[0,1,0] op_sel_hi:[1,1,1]
	v_pk_fma_f32 v[202:203], v[218:219], v[190:191], v[202:203] op_sel:[0,1,0] op_sel_hi:[1,1,1]
	ds_read_b128 v[216:219], v2 offset:60768
	s_waitcnt lgkmcnt(13)
	v_pk_fma_f32 v[204:205], v[220:221], v[190:191], v[204:205] op_sel:[0,1,0] op_sel_hi:[1,1,1]
	v_pk_fma_f32 v[206:207], v[222:223], v[190:191], v[206:207] op_sel:[0,1,0] op_sel_hi:[1,1,1]
	ds_read_b128 v[220:223], v2 offset:60784
	s_waitcnt lgkmcnt(13)
	v_pk_fma_f32 v[192:193], v[224:225], v[192:193], v[192:193] op_sel:[0,0,0] op_sel_hi:[1,0,1]
	v_pk_fma_f32 v[194:195], v[226:227], v[192:193], v[194:195] op_sel:[0,0,0] op_sel_hi:[1,0,1]
	v_cvt_pk_bf16_f32 v3, v192, v2
	ds_write_b16 v113, v3 offset:34560
	ds_read_b128 v[224:227], v2 offset:60880
	s_waitcnt lgkmcnt(14)
	v_pk_fma_f32 v[196:197], v[228:229], v[192:193], v[196:197] op_sel:[0,0,0] op_sel_hi:[1,0,1]
	v_pk_fma_f32 v[198:199], v[230:231], v[192:193], v[198:199] op_sel:[0,0,0] op_sel_hi:[1,0,1]
	ds_read_b128 v[228:231], v2 offset:60896
	s_waitcnt lgkmcnt(14)
	v_pk_fma_f32 v[200:201], v[240:241], v[192:193], v[200:201] op_sel:[0,0,0] op_sel_hi:[1,0,1]
	v_pk_fma_f32 v[202:203], v[242:243], v[192:193], v[202:203] op_sel:[0,0,0] op_sel_hi:[1,0,1]
	ds_read_b128 v[240:243], v2 offset:60912
	s_waitcnt lgkmcnt(13)
	v_pk_fma_f32 v[204:205], v[244:245], v[192:193], v[204:205] op_sel:[0,0,0] op_sel_hi:[1,0,1]
	v_pk_fma_f32 v[206:207], v[246:247], v[192:193], v[206:207] op_sel:[0,0,0] op_sel_hi:[1,0,1]
	ds_read_b128 v[244:247], v2 offset:61008
	s_waitcnt lgkmcnt(13)
	v_pk_fma_f32 v[194:195], v[40:41], v[192:193], v[194:195] op_sel:[0,1,0] op_sel_hi:[1,1,1]
	v_cvt_pk_bf16_f32 v232, v193, v2
	ds_write_b16 v113, v232 offset:34704
	ds_read_b128 v[38:41], v2 offset:61024
	s_waitcnt lgkmcnt(14)
	v_pk_fma_f32 v[196:197], v[42:43], v[192:193], v[196:197] op_sel:[0,1,0] op_sel_hi:[1,1,1]
	v_pk_fma_f32 v[198:199], v[44:45], v[192:193], v[198:199] op_sel:[0,1,0] op_sel_hi:[1,1,1]
	ds_read_b128 v[42:45], v2 offset:61040
	s_waitcnt lgkmcnt(14)
	v_pk_fma_f32 v[200:201], v[46:47], v[192:193], v[200:201] op_sel:[0,1,0] op_sel_hi:[1,1,1]
	v_pk_fma_f32 v[202:203], v[48:49], v[192:193], v[202:203] op_sel:[0,1,0] op_sel_hi:[1,1,1]
	ds_read_b128 v[46:49], v2 offset:61136
	s_waitcnt lgkmcnt(14)
	v_pk_fma_f32 v[204:205], v[50:51], v[192:193], v[204:205] op_sel:[0,1,0] op_sel_hi:[1,1,1]
	v_pk_fma_f32 v[206:207], v[52:53], v[192:193], v[206:207] op_sel:[0,1,0] op_sel_hi:[1,1,1]
	ds_read_b128 v[50:53], v2 offset:61152
	s_waitcnt lgkmcnt(13)
	v_pk_fma_f32 v[194:195], v[210:211], v[194:195], v[194:195] op_sel:[0,0,0] op_sel_hi:[1,0,1]
	v_cvt_pk_bf16_f32 v233, v194, v2
	ds_write_b16 v113, v233 offset:34848
	ds_read_b128 v[208:211], v2 offset:61168
	s_waitcnt lgkmcnt(14)
	v_pk_fma_f32 v[196:197], v[212:213], v[194:195], v[196:197] op_sel:[0,0,0] op_sel_hi:[1,0,1]
	v_pk_fma_f32 v[198:199], v[214:215], v[194:195], v[198:199] op_sel:[0,0,0] op_sel_hi:[1,0,1]
	ds_read_b128 v[212:215], v2 offset:61264
	s_waitcnt lgkmcnt(14)
	v_pk_fma_f32 v[200:201], v[216:217], v[194:195], v[200:201] op_sel:[0,0,0] op_sel_hi:[1,0,1]
	v_pk_fma_f32 v[202:203], v[218:219], v[194:195], v[202:203] op_sel:[0,0,0] op_sel_hi:[1,0,1]
	ds_read_b128 v[216:219], v2 offset:61280
	s_waitcnt lgkmcnt(14)
	v_pk_fma_f32 v[204:205], v[220:221], v[194:195], v[204:205] op_sel:[0,0,0] op_sel_hi:[1,0,1]
	v_pk_fma_f32 v[206:207], v[222:223], v[194:195], v[206:207] op_sel:[0,0,0] op_sel_hi:[1,0,1]
	ds_read_b128 v[220:223], v2 offset:61296
	s_waitcnt lgkmcnt(13)
	v_pk_fma_f32 v[196:197], v[224:225], v[194:195], v[196:197] op_sel:[0,1,0] op_sel_hi:[1,1,1]
	v_pk_fma_f32 v[198:199], v[226:227], v[194:195], v[198:199] op_sel:[0,1,0] op_sel_hi:[1,1,1]
	v_cvt_pk_bf16_f32 v248, v195, v2
	ds_write_b16 v113, v248 offset:34992
	ds_read_b128 v[224:227], v2 offset:61408
	s_waitcnt lgkmcnt(14)
	v_pk_fma_f32 v[200:201], v[228:229], v[194:195], v[200:201] op_sel:[0,1,0] op_sel_hi:[1,1,1]
	v_pk_fma_f32 v[202:203], v[230:231], v[194:195], v[202:203] op_sel:[0,1,0] op_sel_hi:[1,1,1]
	ds_read_b128 v[228:231], v2 offset:61424
	s_waitcnt lgkmcnt(14)
	v_pk_fma_f32 v[204:205], v[240:241], v[194:195], v[204:205] op_sel:[0,1,0] op_sel_hi:[1,1,1]
	v_pk_fma_f32 v[206:207], v[242:243], v[194:195], v[206:207] op_sel:[0,1,0] op_sel_hi:[1,1,1]
	ds_read_b128 v[240:243], v2 offset:61536
	s_waitcnt lgkmcnt(14)
	v_pk_fma_f32 v[196:197], v[244:245], v[196:197], v[196:197] op_sel:[0,0,0] op_sel_hi:[1,0,1]
	v_pk_fma_f32 v[198:199], v[246:247], v[196:197], v[198:199] op_sel:[0,0,0] op_sel_hi:[1,0,1]
	v_cvt_pk_bf16_f32 v3, v196, v2
	ds_write_b16 v113, v3 offset:35136
	s_waitcnt lgkmcnt(14)
	ds_read_b128 v[244:247], v2 offset:61552
	s_waitcnt lgkmcnt(14)
	v_pk_fma_f32 v[200:201], v[38:39], v[196:197], v[200:201] op_sel:[0,0,0] op_sel_hi:[1,0,1]
	v_pk_fma_f32 v[202:203], v[40:41], v[196:197], v[202:203] op_sel:[0,0,0] op_sel_hi:[1,0,1]
	ds_read_b128 v[38:41], v2 offset:61664
	s_waitcnt lgkmcnt(14)
	v_pk_fma_f32 v[204:205], v[42:43], v[196:197], v[204:205] op_sel:[0,0,0] op_sel_hi:[1,0,1]
	v_pk_fma_f32 v[206:207], v[44:45], v[196:197], v[206:207] op_sel:[0,0,0] op_sel_hi:[1,0,1]
	ds_read_b128 v[42:45], v2 offset:61680
	s_waitcnt lgkmcnt(14)
	v_pk_fma_f32 v[198:199], v[48:49], v[196:197], v[198:199] op_sel:[0,1,0] op_sel_hi:[1,1,1]
	v_cvt_pk_bf16_f32 v232, v197, v2
	ds_write_b16 v113, v232 offset:35280
	s_waitcnt lgkmcnt(14)
	ds_read_b128 v[46:49], v2 offset:61792
	v_pk_fma_f32 v[200:201], v[50:51], v[196:197], v[200:201] op_sel:[0,1,0] op_sel_hi:[1,1,1]
	v_pk_fma_f32 v[202:203], v[52:53], v[196:197], v[202:203] op_sel:[0,1,0] op_sel_hi:[1,1,1]
	s_waitcnt lgkmcnt(14)
	ds_read_b128 v[50:53], v2 offset:61808
	s_waitcnt lgkmcnt(14)
	v_pk_fma_f32 v[204:205], v[208:209], v[196:197], v[204:205] op_sel:[0,1,0] op_sel_hi:[1,1,1]
	v_pk_fma_f32 v[206:207], v[210:211], v[196:197], v[206:207] op_sel:[0,1,0] op_sel_hi:[1,1,1]
	ds_read_b128 v[208:211], v2 offset:61936
	s_waitcnt lgkmcnt(14)
	v_pk_fma_f32 v[198:199], v[214:215], v[198:199], v[198:199] op_sel:[0,0,0] op_sel_hi:[1,0,1]
	v_cvt_pk_bf16_f32 v233, v198, v2
	ds_write_b16 v113, v233 offset:35424
	s_waitcnt lgkmcnt(14)
	ds_read_b128 v[212:215], v2 offset:62064
	v_pk_fma_f32 v[200:201], v[216:217], v[198:199], v[200:201] op_sel:[0,0,0] op_sel_hi:[1,0,1]
	v_pk_fma_f32 v[202:203], v[218:219], v[198:199], v[202:203] op_sel:[0,0,0] op_sel_hi:[1,0,1]
	s_waitcnt lgkmcnt(14)
	ds_read_b128 v[216:219], v2 offset:62192
	v_pk_fma_f32 v[204:205], v[220:221], v[198:199], v[204:205] op_sel:[0,0,0] op_sel_hi:[1,0,1]
	v_pk_fma_f32 v[206:207], v[222:223], v[198:199], v[206:207] op_sel:[0,0,0] op_sel_hi:[1,0,1]
	s_waitcnt lgkmcnt(14)
	ds_read_b128 v[220:223], v2 offset:62320
	s_waitcnt lgkmcnt(14)
	v_pk_fma_f32 v[200:201], v[224:225], v[198:199], v[200:201] op_sel:[0,1,0] op_sel_hi:[1,1,1]
	v_pk_fma_f32 v[202:203], v[226:227], v[198:199], v[202:203] op_sel:[0,1,0] op_sel_hi:[1,1,1]
	v_cvt_pk_bf16_f32 v248, v199, v2
	ds_write_b16 v113, v248 offset:35568
	s_waitcnt lgkmcnt(14)
	v_pk_fma_f32 v[204:205], v[228:229], v[198:199], v[204:205] op_sel:[0,1,0] op_sel_hi:[1,1,1]
	v_pk_fma_f32 v[206:207], v[230:231], v[198:199], v[206:207] op_sel:[0,1,0] op_sel_hi:[1,1,1]
	s_waitcnt lgkmcnt(13)
	v_pk_fma_f32 v[200:201], v[240:241], v[200:201], v[200:201] op_sel:[0,0,0] op_sel_hi:[1,0,1]
	v_pk_fma_f32 v[202:203], v[242:243], v[200:201], v[202:203] op_sel:[0,0,0] op_sel_hi:[1,0,1]
	v_cvt_pk_bf16_f32 v3, v200, v2
	ds_write_b16 v113, v3 offset:35712
	s_waitcnt lgkmcnt(12)
	v_pk_fma_f32 v[204:205], v[244:245], v[200:201], v[204:205] op_sel:[0,0,0] op_sel_hi:[1,0,1]
	v_pk_fma_f32 v[206:207], v[246:247], v[200:201], v[206:207] op_sel:[0,0,0] op_sel_hi:[1,0,1]
	s_waitcnt lgkmcnt(11)
	v_pk_fma_f32 v[202:203], v[40:41], v[200:201], v[202:203] op_sel:[0,1,0] op_sel_hi:[1,1,1]
	v_cvt_pk_bf16_f32 v232, v201, v2
	ds_write_b16 v113, v232 offset:35856
	s_waitcnt lgkmcnt(11)
	v_pk_fma_f32 v[204:205], v[42:43], v[200:201], v[204:205] op_sel:[0,1,0] op_sel_hi:[1,1,1]
	v_pk_fma_f32 v[206:207], v[44:45], v[200:201], v[206:207] op_sel:[0,1,0] op_sel_hi:[1,1,1]
	s_waitcnt lgkmcnt(9)
	v_pk_fma_f32 v[202:203], v[48:49], v[202:203], v[202:203] op_sel:[0,0,0] op_sel_hi:[1,0,1]
	v_cvt_pk_bf16_f32 v233, v202, v2
	ds_write_b16 v113, v233 offset:36000
	s_waitcnt lgkmcnt(9)
	v_pk_fma_f32 v[204:205], v[50:51], v[202:203], v[204:205] op_sel:[0,0,0] op_sel_hi:[1,0,1]
	v_pk_fma_f32 v[206:207], v[52:53], v[202:203], v[206:207] op_sel:[0,0,0] op_sel_hi:[1,0,1]
	s_waitcnt lgkmcnt(8)
	v_pk_fma_f32 v[204:205], v[208:209], v[202:203], v[204:205] op_sel:[0,1,0] op_sel_hi:[1,1,1]
	v_pk_fma_f32 v[206:207], v[210:211], v[202:203], v[206:207] op_sel:[0,1,0] op_sel_hi:[1,1,1]
	v_cvt_pk_bf16_f32 v248, v203, v2
	ds_write_b16 v113, v248 offset:36144
	s_waitcnt lgkmcnt(7)
	v_pk_fma_f32 v[204:205], v[212:213], v[204:205], v[204:205] op_sel:[0,0,0] op_sel_hi:[1,0,1]
	v_pk_fma_f32 v[206:207], v[214:215], v[204:205], v[206:207] op_sel:[0,0,0] op_sel_hi:[1,0,1]
	v_cvt_pk_bf16_f32 v3, v204, v2
	ds_write_b16 v113, v3 offset:36288
	s_waitcnt lgkmcnt(7)
	v_pk_fma_f32 v[206:207], v[218:219], v[204:205], v[206:207] op_sel:[0,1,0] op_sel_hi:[1,1,1]
	v_cvt_pk_bf16_f32 v232, v205, v2
	ds_write_b16 v113, v232 offset:36432
	s_waitcnt lgkmcnt(7)
	v_pk_fma_f32 v[206:207], v[222:223], v[206:207], v[206:207] op_sel:[0,0,0] op_sel_hi:[1,0,1]
	v_cvt_pk_bf16_f32 v233, v206, v2
	ds_write_b16 v113, v233 offset:36576
	v_cvt_pk_bf16_f32 v248, v207, v2
	ds_write_b16 v113, v248 offset:36720
